# sample-row tiles of out-proj B and both PLE phases spread one per workgroup over 128 workgroups; write-through stores in out-proj epilogues
# speedup vs baseline: 1.0139x; 1.0130x over previous
.LBB0_497:
	ds_read_b128 v[152:155], v147
	ds_read_b128 v[156:159], v147 offset:1024
	ds_read_b128 v[160:163], v147 offset:2048
	ds_read_b128 v[164:167], v147 offset:3072
	s_add_u32 s20, s18, 0xfff80080
	s_addc_u32 s21, s19, -1
	s_cmp_eq_u32 s55, 28
	s_cselect_b32 s23, s11, s21
	s_cselect_b32 s22, s51, s20
	s_cselect_b32 s21, s7, s54
	s_cselect_b32 s20, s52, s53
	v_lshl_add_u64 v[200:201], s[18:19], 0, v[138:139]
	s_add_i32 m0, s33, 0xc000
	ds_read_b128 v[168:171], v148
	ds_read_b128 v[172:175], v148 offset:1024
	ds_read_b128 v[176:179], v148 offset:2048
	ds_read_b128 v[180:183], v148 offset:3072
	ds_read_b128 v[184:187], v148 offset:4096
	ds_read_b128 v[188:191], v148 offset:5120
	ds_read_b128 v[192:195], v148 offset:6144
	ds_read_b128 v[196:199], v148 offset:7168
	global_load_lds_dwordx4 v[200:201], off
	v_lshl_add_u64 v[200:201], s[18:19], 0, v[140:141]
	s_add_i32 m0, s33, 0xe000
	s_nop 0
	global_load_lds_dwordx4 v[200:201], off
	s_waitcnt lgkmcnt(8)
	s_barrier
	s_waitcnt lgkmcnt(0)
	s_setprio 1
	s_waitcnt lgkmcnt(0)
	v_mfma_f32_16x16x32_bf16 v[124:127], v[152:155], v[168:171], v[124:127]
	v_mfma_f32_16x16x32_bf16 v[120:123], v[160:163], v[168:171], v[120:123]
	v_mfma_f32_16x16x32_bf16 v[112:115], v[152:155], v[176:179], v[112:115]
	v_mfma_f32_16x16x32_bf16 v[104:107], v[160:163], v[176:179], v[104:107]
	v_mfma_f32_16x16x32_bf16 v[100:103], v[152:155], v[184:187], v[100:103]
	v_mfma_f32_16x16x32_bf16 v[96:99], v[160:163], v[184:187], v[96:99]
	v_mfma_f32_16x16x32_bf16 v[84:87], v[152:155], v[192:195], v[84:87]
	v_mfma_f32_16x16x32_bf16 v[80:83], v[160:163], v[192:195], v[80:83]
	v_mfma_f32_16x16x32_bf16 v[124:127], v[156:159], v[172:175], v[124:127]
	v_mfma_f32_16x16x32_bf16 v[120:123], v[164:167], v[172:175], v[120:123]
	v_mfma_f32_16x16x32_bf16 v[112:115], v[156:159], v[180:183], v[112:115]
	v_mfma_f32_16x16x32_bf16 v[104:107], v[164:167], v[180:183], v[104:107]
	v_mfma_f32_16x16x32_bf16 v[100:103], v[156:159], v[188:191], v[100:103]
	v_mfma_f32_16x16x32_bf16 v[96:99], v[164:167], v[188:191], v[96:99]
	v_mfma_f32_16x16x32_bf16 v[84:87], v[156:159], v[196:199], v[84:87]
	v_mfma_f32_16x16x32_bf16 v[80:83], v[164:167], v[196:199], v[80:83]
	s_setprio 0
	s_barrier
	s_mov_b32 m0, s13
	v_lshl_add_u64 v[216:217], s[20:21], 0, v[130:131]
	ds_read_b128 v[200:203], v149
	ds_read_b128 v[204:207], v149 offset:1024
	ds_read_b128 v[208:211], v149 offset:2048
	ds_read_b128 v[212:215], v149 offset:3072
	global_load_lds_dwordx4 v[216:217], off
	v_lshl_add_u64 v[218:219], s[20:21], 0, v[134:135]
	s_mov_b32 m0, s31
	s_nop 0
	global_load_lds_dwordx4 v[218:219], off
	s_barrier
	s_waitcnt lgkmcnt(0)
	s_setprio 1
	s_waitcnt lgkmcnt(0)
	v_mfma_f32_16x16x32_bf16 v[116:119], v[200:203], v[168:171], v[116:119]
	v_mfma_f32_16x16x32_bf16 v[108:111], v[208:211], v[168:171], v[108:111]
	v_mfma_f32_16x16x32_bf16 v[92:95], v[200:203], v[176:179], v[92:95]
	v_mfma_f32_16x16x32_bf16 v[88:91], v[208:211], v[176:179], v[88:91]
	v_mfma_f32_16x16x32_bf16 v[76:79], v[200:203], v[184:187], v[76:79]
	v_mfma_f32_16x16x32_bf16 v[72:75], v[208:211], v[184:187], v[72:75]
	v_mfma_f32_16x16x32_bf16 v[68:71], v[200:203], v[192:195], v[68:71]
	v_mfma_f32_16x16x32_bf16 v[64:67], v[208:211], v[192:195], v[64:67]
	v_mfma_f32_16x16x32_bf16 v[116:119], v[204:207], v[172:175], v[116:119]
	v_mfma_f32_16x16x32_bf16 v[108:111], v[212:215], v[172:175], v[108:111]
	v_mfma_f32_16x16x32_bf16 v[92:95], v[204:207], v[180:183], v[92:95]
	v_mfma_f32_16x16x32_bf16 v[88:91], v[212:215], v[180:183], v[88:91]
	v_mfma_f32_16x16x32_bf16 v[76:79], v[204:207], v[188:191], v[76:79]
	v_mfma_f32_16x16x32_bf16 v[72:75], v[212:215], v[188:191], v[72:75]
	v_mfma_f32_16x16x32_bf16 v[68:71], v[204:207], v[196:199], v[68:71]
	v_mfma_f32_16x16x32_bf16 v[64:67], v[212:215], v[196:199], v[64:67]
	s_setprio 0
	s_mov_b32 m0, s33
	v_lshl_add_u64 v[220:221], s[22:23], 0, v[128:129]
	s_barrier
	ds_read_b128 v[168:171], v148 offset:16384
	ds_read_b128 v[172:175], v148 offset:17408
	ds_read_b128 v[176:179], v148 offset:18432
	ds_read_b128 v[180:183], v148 offset:19456
	ds_read_b128 v[184:187], v148 offset:20480
	ds_read_b128 v[188:191], v148 offset:21504
	ds_read_b128 v[192:195], v148 offset:22528
	ds_read_b128 v[196:199], v148 offset:23552
	global_load_lds_dwordx4 v[220:221], off
	v_lshl_add_u64 v[222:223], s[22:23], 0, v[132:133]
	s_mov_b32 m0, s34
	s_nop 0
	global_load_lds_dwordx4 v[222:223], off
	s_barrier
	s_waitcnt lgkmcnt(0)
	s_setprio 1
	s_waitcnt lgkmcnt(0)
	v_mfma_f32_16x16x32_bf16 v[60:63], v[152:155], v[168:171], v[60:63]
	v_mfma_f32_16x16x32_bf16 v[56:59], v[160:163], v[168:171], v[56:59]
	v_mfma_f32_16x16x32_bf16 v[52:55], v[152:155], v[176:179], v[52:55]
	v_mfma_f32_16x16x32_bf16 v[48:51], v[160:163], v[176:179], v[48:51]
	v_mfma_f32_16x16x32_bf16 v[36:39], v[152:155], v[184:187], v[36:39]
	v_mfma_f32_16x16x32_bf16 v[32:35], v[160:163], v[184:187], v[32:35]
	v_mfma_f32_16x16x32_bf16 v[20:23], v[152:155], v[192:195], v[20:23]
	v_mfma_f32_16x16x32_bf16 v[16:19], v[160:163], v[192:195], v[16:19]
	v_mfma_f32_16x16x32_bf16 v[60:63], v[156:159], v[172:175], v[60:63]
	v_mfma_f32_16x16x32_bf16 v[56:59], v[164:167], v[172:175], v[56:59]
	v_mfma_f32_16x16x32_bf16 v[52:55], v[156:159], v[180:183], v[52:55]
	v_mfma_f32_16x16x32_bf16 v[48:51], v[164:167], v[180:183], v[48:51]
	v_mfma_f32_16x16x32_bf16 v[36:39], v[156:159], v[188:191], v[36:39]
	v_mfma_f32_16x16x32_bf16 v[32:35], v[164:167], v[188:191], v[32:35]
	v_mfma_f32_16x16x32_bf16 v[20:23], v[156:159], v[196:199], v[20:23]
	v_mfma_f32_16x16x32_bf16 v[16:19], v[164:167], v[196:199], v[16:19]
	s_setprio 0
	s_barrier
	s_add_u32 s56, s20, 0x80000
	s_addc_u32 s57, s21, 0
	s_mov_b32 m0, s35
	v_lshl_add_u64 v[152:153], s[56:57], 0, v[130:131]
	global_load_lds_dwordx4 v[152:153], off
	v_lshl_add_u64 v[152:153], s[56:57], 0, v[134:135]
	s_mov_b32 m0, s36
	s_nop 0
	global_load_lds_dwordx4 v[152:153], off
	s_waitcnt vmcnt(6)
	s_barrier
	s_setprio 1
	v_mfma_f32_16x16x32_bf16 v[44:47], v[200:203], v[168:171], v[44:47]
	v_mfma_f32_16x16x32_bf16 v[40:43], v[208:211], v[168:171], v[40:43]
	v_mfma_f32_16x16x32_bf16 v[28:31], v[200:203], v[176:179], v[28:31]
	v_mfma_f32_16x16x32_bf16 v[24:27], v[208:211], v[176:179], v[24:27]
	v_mfma_f32_16x16x32_bf16 v[12:15], v[200:203], v[184:187], v[12:15]
	v_mfma_f32_16x16x32_bf16 v[8:11], v[208:211], v[184:187], v[8:11]
	v_mfma_f32_16x16x32_bf16 v[4:7], v[200:203], v[192:195], v[4:7]
	v_mfma_f32_16x16x32_bf16 v[0:3], v[208:211], v[192:195], v[0:3]
	v_mfma_f32_16x16x32_bf16 v[44:47], v[204:207], v[172:175], v[44:47]
	v_mfma_f32_16x16x32_bf16 v[40:43], v[212:215], v[172:175], v[40:43]
	v_mfma_f32_16x16x32_bf16 v[28:31], v[204:207], v[180:183], v[28:31]
	v_mfma_f32_16x16x32_bf16 v[24:27], v[212:215], v[180:183], v[24:27]
	v_mfma_f32_16x16x32_bf16 v[12:15], v[204:207], v[188:191], v[12:15]
	v_mfma_f32_16x16x32_bf16 v[8:11], v[212:215], v[188:191], v[8:11]
	v_mfma_f32_16x16x32_bf16 v[4:7], v[204:207], v[196:199], v[4:7]
	v_mfma_f32_16x16x32_bf16 v[0:3], v[212:215], v[196:199], v[0:3]
	s_setprio 0
	s_barrier
	ds_read_b128 v[152:155], v150
	ds_read_b128 v[156:159], v150 offset:1024
	ds_read_b128 v[160:163], v150 offset:2048
	ds_read_b128 v[164:167], v150 offset:3072
	s_add_u32 s22, s22, 0x80000
	s_addc_u32 s23, s23, 0
	s_mov_b32 m0, s37
	v_lshl_add_u64 v[200:201], s[22:23], 0, v[128:129]
	ds_read_b128 v[168:171], v148 offset:32768
	ds_read_b128 v[172:175], v148 offset:33792
	ds_read_b128 v[176:179], v148 offset:34816
	ds_read_b128 v[180:183], v148 offset:35840
	ds_read_b128 v[184:187], v148 offset:36864
	ds_read_b128 v[188:191], v148 offset:37888
	ds_read_b128 v[192:195], v148 offset:38912
	ds_read_b128 v[196:199], v148 offset:39936
	global_load_lds_dwordx4 v[200:201], off
	v_lshl_add_u64 v[200:201], s[22:23], 0, v[132:133]
	s_mov_b32 m0, s38
	s_nop 0
	global_load_lds_dwordx4 v[200:201], off
	s_waitcnt lgkmcnt(8)
	s_barrier
	s_waitcnt lgkmcnt(0)
	s_setprio 1
	s_waitcnt lgkmcnt(0)
	v_mfma_f32_16x16x32_bf16 v[124:127], v[152:155], v[168:171], v[124:127]
	v_mfma_f32_16x16x32_bf16 v[120:123], v[160:163], v[168:171], v[120:123]
	v_mfma_f32_16x16x32_bf16 v[112:115], v[152:155], v[176:179], v[112:115]
	v_mfma_f32_16x16x32_bf16 v[104:107], v[160:163], v[176:179], v[104:107]
	v_mfma_f32_16x16x32_bf16 v[100:103], v[152:155], v[184:187], v[100:103]
	v_mfma_f32_16x16x32_bf16 v[96:99], v[160:163], v[184:187], v[96:99]
	v_mfma_f32_16x16x32_bf16 v[84:87], v[152:155], v[192:195], v[84:87]
	v_mfma_f32_16x16x32_bf16 v[80:83], v[160:163], v[192:195], v[80:83]
	v_mfma_f32_16x16x32_bf16 v[124:127], v[156:159], v[172:175], v[124:127]
	v_mfma_f32_16x16x32_bf16 v[120:123], v[164:167], v[172:175], v[120:123]
	v_mfma_f32_16x16x32_bf16 v[112:115], v[156:159], v[180:183], v[112:115]
	v_mfma_f32_16x16x32_bf16 v[104:107], v[164:167], v[180:183], v[104:107]
	v_mfma_f32_16x16x32_bf16 v[100:103], v[156:159], v[188:191], v[100:103]
	v_mfma_f32_16x16x32_bf16 v[96:99], v[164:167], v[188:191], v[96:99]
	v_mfma_f32_16x16x32_bf16 v[84:87], v[156:159], v[196:199], v[84:87]
	v_mfma_f32_16x16x32_bf16 v[80:83], v[164:167], v[196:199], v[80:83]
	s_setprio 0
	s_barrier
	s_mov_b32 m0, s42
	v_lshl_add_u64 v[216:217], v[216:217], 0, s[4:5]
	ds_read_b128 v[200:203], v151
	ds_read_b128 v[204:207], v151 offset:1024
	ds_read_b128 v[208:211], v151 offset:2048
	ds_read_b128 v[212:215], v151 offset:3072
	global_load_lds_dwordx4 v[216:217], off
	v_lshl_add_u64 v[216:217], v[218:219], 0, s[4:5]
	s_mov_b32 m0, s43
	s_nop 0
	global_load_lds_dwordx4 v[216:217], off
	s_barrier
	s_waitcnt lgkmcnt(0)
	s_setprio 1
	s_waitcnt lgkmcnt(0)
	v_mfma_f32_16x16x32_bf16 v[116:119], v[200:203], v[168:171], v[116:119]
	v_mfma_f32_16x16x32_bf16 v[108:111], v[208:211], v[168:171], v[108:111]
	v_mfma_f32_16x16x32_bf16 v[92:95], v[200:203], v[176:179], v[92:95]
	v_mfma_f32_16x16x32_bf16 v[88:91], v[208:211], v[176:179], v[88:91]
	v_mfma_f32_16x16x32_bf16 v[76:79], v[200:203], v[184:187], v[76:79]
	v_mfma_f32_16x16x32_bf16 v[72:75], v[208:211], v[184:187], v[72:75]
	v_mfma_f32_16x16x32_bf16 v[68:71], v[200:203], v[192:195], v[68:71]
	v_mfma_f32_16x16x32_bf16 v[64:67], v[208:211], v[192:195], v[64:67]
	v_mfma_f32_16x16x32_bf16 v[116:119], v[204:207], v[172:175], v[116:119]
	v_mfma_f32_16x16x32_bf16 v[108:111], v[212:215], v[172:175], v[108:111]
	v_mfma_f32_16x16x32_bf16 v[92:95], v[204:207], v[180:183], v[92:95]
	v_mfma_f32_16x16x32_bf16 v[88:91], v[212:215], v[180:183], v[88:91]
	v_mfma_f32_16x16x32_bf16 v[76:79], v[204:207], v[188:191], v[76:79]
	v_mfma_f32_16x16x32_bf16 v[72:75], v[212:215], v[188:191], v[72:75]
	v_mfma_f32_16x16x32_bf16 v[68:71], v[204:207], v[196:199], v[68:71]
	v_mfma_f32_16x16x32_bf16 v[64:67], v[212:215], v[196:199], v[64:67]
	s_setprio 0
	s_mov_b32 m0, s44
	v_lshl_add_u64 v[216:217], v[220:221], 0, s[4:5]
	s_barrier
	ds_read_b128 v[168:171], v148 offset:49152
	ds_read_b128 v[172:175], v148 offset:50176
	ds_read_b128 v[176:179], v148 offset:51200
	ds_read_b128 v[180:183], v148 offset:52224
	ds_read_b128 v[184:187], v148 offset:53248
	ds_read_b128 v[188:191], v148 offset:54272
	ds_read_b128 v[192:195], v148 offset:55296
	ds_read_b128 v[196:199], v148 offset:56320
	global_load_lds_dwordx4 v[216:217], off
	v_lshl_add_u64 v[216:217], v[222:223], 0, s[4:5]
	s_mov_b32 m0, s45
	s_nop 0
	global_load_lds_dwordx4 v[216:217], off
	s_barrier
	s_waitcnt lgkmcnt(0)
	s_setprio 1
	s_waitcnt lgkmcnt(0)
	v_mfma_f32_16x16x32_bf16 v[60:63], v[152:155], v[168:171], v[60:63]
	v_mfma_f32_16x16x32_bf16 v[56:59], v[160:163], v[168:171], v[56:59]
	v_mfma_f32_16x16x32_bf16 v[52:55], v[152:155], v[176:179], v[52:55]
	v_mfma_f32_16x16x32_bf16 v[48:51], v[160:163], v[176:179], v[48:51]
	v_mfma_f32_16x16x32_bf16 v[36:39], v[152:155], v[184:187], v[36:39]
	v_mfma_f32_16x16x32_bf16 v[32:35], v[160:163], v[184:187], v[32:35]
	v_mfma_f32_16x16x32_bf16 v[20:23], v[152:155], v[192:195], v[20:23]
	v_mfma_f32_16x16x32_bf16 v[16:19], v[160:163], v[192:195], v[16:19]
	v_mfma_f32_16x16x32_bf16 v[60:63], v[156:159], v[172:175], v[60:63]
	v_mfma_f32_16x16x32_bf16 v[56:59], v[164:167], v[172:175], v[56:59]
	v_mfma_f32_16x16x32_bf16 v[52:55], v[156:159], v[180:183], v[52:55]
	v_mfma_f32_16x16x32_bf16 v[48:51], v[164:167], v[180:183], v[48:51]
	v_mfma_f32_16x16x32_bf16 v[36:39], v[156:159], v[188:191], v[36:39]
	v_mfma_f32_16x16x32_bf16 v[32:35], v[164:167], v[188:191], v[32:35]
	v_mfma_f32_16x16x32_bf16 v[20:23], v[156:159], v[196:199], v[20:23]
	v_mfma_f32_16x16x32_bf16 v[16:19], v[164:167], v[196:199], v[16:19]
	s_setprio 0
	s_barrier
	s_add_u32 s20, s20, 0x80080
	s_addc_u32 s21, s21, 0
	s_mov_b32 m0, s46
	v_lshl_add_u64 v[152:153], s[20:21], 0, v[130:131]
	global_load_lds_dwordx4 v[152:153], off
	v_lshl_add_u64 v[152:153], s[20:21], 0, v[134:135]
	s_mov_b32 m0, s47
	s_nop 0
	global_load_lds_dwordx4 v[152:153], off
	s_waitcnt vmcnt(6)
	s_barrier
	s_setprio 1
	v_mfma_f32_16x16x32_bf16 v[44:47], v[200:203], v[168:171], v[44:47]
	v_mfma_f32_16x16x32_bf16 v[40:43], v[208:211], v[168:171], v[40:43]
	v_mfma_f32_16x16x32_bf16 v[28:31], v[200:203], v[176:179], v[28:31]
	v_mfma_f32_16x16x32_bf16 v[24:27], v[208:211], v[176:179], v[24:27]
	v_mfma_f32_16x16x32_bf16 v[12:15], v[200:203], v[184:187], v[12:15]
	v_mfma_f32_16x16x32_bf16 v[8:11], v[208:211], v[184:187], v[8:11]
	v_mfma_f32_16x16x32_bf16 v[4:7], v[200:203], v[192:195], v[4:7]
	v_mfma_f32_16x16x32_bf16 v[0:3], v[208:211], v[192:195], v[0:3]
	v_mfma_f32_16x16x32_bf16 v[44:47], v[204:207], v[172:175], v[44:47]
	v_mfma_f32_16x16x32_bf16 v[40:43], v[212:215], v[172:175], v[40:43]
	v_mfma_f32_16x16x32_bf16 v[28:31], v[204:207], v[180:183], v[28:31]
	v_mfma_f32_16x16x32_bf16 v[24:27], v[212:215], v[180:183], v[24:27]
	v_mfma_f32_16x16x32_bf16 v[12:15], v[204:207], v[188:191], v[12:15]
	v_mfma_f32_16x16x32_bf16 v[8:11], v[212:215], v[188:191], v[8:11]
	v_mfma_f32_16x16x32_bf16 v[4:7], v[204:207], v[196:199], v[4:7]
	v_mfma_f32_16x16x32_bf16 v[0:3], v[212:215], v[196:199], v[0:3]
	s_setprio 0
	s_add_i32 s55, s55, 2
	s_add_u32 s18, s18, 0x100
	s_addc_u32 s19, s19, 0
	s_add_u32 s53, s53, 0x100
	s_addc_u32 s54, s54, 0
	s_cmp_gt_u32 s55, 29
	s_barrier
	s_cbranch_scc0 .LBB0_497
	v_mov_b32_e32 v136, 0
	s_lshl_b32 s7, s12, 8
	v_mbcnt_lo_u32_b32 v136, -1, v136
	v_mbcnt_hi_u32_b32 v136, -1, v136
	s_add_i32 s7, s7, s40
	v_and_or_b32 v152, v136, 15, s7
	s_lshl_b32 s7, s50, 8
	v_ashrrev_i32_e32 v136, 1, v136
	v_and_b32_e32 v136, -8, v136
	s_or_b32 s7, s7, s41
	v_add_u32_e32 v154, s7, v136
	v_cvt_pk_bf16_f32 v124, v124, v125
	v_cvt_pk_bf16_f32 v125, v126, v127
	v_cvt_pk_bf16_f32 v126, v120, v121
	v_lshrrev_b32_e32 v120, 8, v154
	v_ashrrev_i32_e32 v153, 31, v152
	v_mul_hi_i32_i24_e32 v121, 0x4080, v120
	v_mul_i32_i24_e32 v120, 0x4080, v120
	v_cvt_pk_bf16_f32 v127, v122, v123
	v_lshl_add_u64 v[122:123], v[120:121], 0, v[152:153]
	v_and_b32_e32 v136, 0xf8, v154
	v_lshlrev_b64 v[122:123], 9, v[122:123]
	v_lshl_add_u64 v[122:123], s[0:1], 0, v[122:123]
	v_lshlrev_b32_e32 v136, 1, v136
	v_lshl_add_u64 v[122:123], v[122:123], 0, v[136:137]
	global_store_dwordx4 v[122:123], v[124:127], off sc1
	v_cvt_pk_bf16_f32 v116, v116, v117
	v_cvt_pk_bf16_f32 v117, v118, v119
	v_add_u32_e32 v124, 0x80, v154
	v_cvt_pk_bf16_f32 v118, v108, v109
	v_lshrrev_b32_e32 v108, 8, v124
	v_mul_hi_i32_i24_e32 v123, 0x4080, v108
	v_mul_i32_i24_e32 v122, 0x4080, v108
	v_lshl_add_u64 v[108:109], v[122:123], 0, v[152:153]
	v_cvt_pk_bf16_f32 v119, v110, v111
	v_and_b32_e32 v110, 0xf8, v124
	v_lshlrev_b64 v[108:109], 9, v[108:109]
	v_lshl_add_u64 v[108:109], s[0:1], 0, v[108:109]
	v_lshlrev_b32_e32 v124, 1, v110
	v_mov_b32_e32 v125, v137
	v_lshl_add_u64 v[108:109], v[108:109], 0, v[124:125]
	global_store_dwordx4 v[108:109], v[116:119], off sc1
	v_cvt_pk_bf16_f32 v110, v104, v105
	v_cvt_pk_bf16_f32 v92, v92, v93
	v_or_b32_e32 v116, 16, v152
	v_ashrrev_i32_e32 v117, 31, v116
	v_lshl_add_u64 v[104:105], v[120:121], 0, v[116:117]
	v_cvt_pk_bf16_f32 v93, v94, v95
	v_cvt_pk_bf16_f32 v94, v88, v89
	v_lshl_add_u64 v[88:89], v[122:123], 0, v[116:117]
	v_lshlrev_b64 v[104:105], 9, v[104:105]
	v_lshlrev_b64 v[88:89], 9, v[88:89]
	v_lshl_add_u64 v[104:105], s[0:1], 0, v[104:105]
	v_lshl_add_u64 v[88:89], s[0:1], 0, v[88:89]
	v_cvt_pk_bf16_f32 v108, v112, v113
	v_cvt_pk_bf16_f32 v109, v114, v115
	v_cvt_pk_bf16_f32 v111, v106, v107
	v_lshl_add_u64 v[104:105], v[104:105], 0, v[136:137]
	v_cvt_pk_bf16_f32 v95, v90, v91
	v_lshl_add_u64 v[88:89], v[88:89], 0, v[124:125]
	global_store_dwordx4 v[104:105], v[108:111], off sc1
	global_store_dwordx4 v[88:89], v[92:95], off sc1
	v_cvt_pk_bf16_f32 v76, v76, v77
	v_cvt_pk_bf16_f32 v77, v78, v79
	v_or_b32_e32 v92, 32, v152
	v_ashrrev_i32_e32 v93, 31, v92
	v_lshl_add_u64 v[94:95], v[120:121], 0, v[92:93]
	v_cvt_pk_bf16_f32 v78, v72, v73
	v_lshl_add_u64 v[72:73], v[122:123], 0, v[92:93]
	v_lshlrev_b64 v[94:95], 9, v[94:95]
	v_lshlrev_b64 v[72:73], 9, v[72:73]
	v_lshl_add_u64 v[94:95], s[0:1], 0, v[94:95]
	v_lshl_add_u64 v[72:73], s[0:1], 0, v[72:73]
	v_cvt_pk_bf16_f32 v88, v100, v101
	v_cvt_pk_bf16_f32 v89, v102, v103
	v_cvt_pk_bf16_f32 v90, v96, v97
	v_cvt_pk_bf16_f32 v91, v98, v99
	v_lshl_add_u64 v[94:95], v[94:95], 0, v[136:137]
	v_cvt_pk_bf16_f32 v79, v74, v75
	v_lshl_add_u64 v[72:73], v[72:73], 0, v[124:125]
	global_store_dwordx4 v[94:95], v[88:91], off sc1
	global_store_dwordx4 v[72:73], v[76:79], off sc1
	v_cvt_pk_bf16_f32 v68, v68, v69
	v_cvt_pk_bf16_f32 v69, v70, v71
	v_or_b32_e32 v76, 48, v152
	v_ashrrev_i32_e32 v77, 31, v76
	v_lshl_add_u64 v[78:79], v[120:121], 0, v[76:77]
	v_cvt_pk_bf16_f32 v70, v64, v65
	v_lshl_add_u64 v[64:65], v[122:123], 0, v[76:77]
	v_lshlrev_b64 v[78:79], 9, v[78:79]
	v_lshlrev_b64 v[64:65], 9, v[64:65]
	v_lshl_add_u64 v[78:79], s[0:1], 0, v[78:79]
	v_lshl_add_u64 v[64:65], s[0:1], 0, v[64:65]
	v_cvt_pk_bf16_f32 v72, v84, v85
	v_cvt_pk_bf16_f32 v73, v86, v87
	v_cvt_pk_bf16_f32 v74, v80, v81
	v_cvt_pk_bf16_f32 v75, v82, v83
	v_lshl_add_u64 v[78:79], v[78:79], 0, v[136:137]
	v_cvt_pk_bf16_f32 v71, v66, v67
	v_lshl_add_u64 v[64:65], v[64:65], 0, v[124:125]
	global_store_dwordx4 v[78:79], v[72:75], off sc1
	global_store_dwordx4 v[64:65], v[68:71], off sc1
	v_add_u32_e32 v64, 0x80, v152
	v_ashrrev_i32_e32 v65, 31, v64
	v_cvt_pk_bf16_f32 v60, v60, v61
	v_cvt_pk_bf16_f32 v61, v62, v63
	v_cvt_pk_bf16_f32 v62, v56, v57
	v_lshl_add_u64 v[56:57], v[120:121], 0, v[64:65]
	v_cvt_pk_bf16_f32 v44, v44, v45
	v_cvt_pk_bf16_f32 v45, v46, v47
	v_cvt_pk_bf16_f32 v46, v40, v41
	v_lshl_add_u64 v[40:41], v[122:123], 0, v[64:65]
	v_lshlrev_b64 v[56:57], 9, v[56:57]
	v_lshlrev_b64 v[40:41], 9, v[40:41]
	v_lshl_add_u64 v[56:57], s[0:1], 0, v[56:57]
	v_lshl_add_u64 v[40:41], s[0:1], 0, v[40:41]
	v_cvt_pk_bf16_f32 v63, v58, v59
	v_lshl_add_u64 v[56:57], v[56:57], 0, v[136:137]
	v_cvt_pk_bf16_f32 v47, v42, v43
	v_lshl_add_u64 v[40:41], v[40:41], 0, v[124:125]
	global_store_dwordx4 v[56:57], v[60:63], off sc1
	global_store_dwordx4 v[40:41], v[44:47], off sc1
	v_cvt_pk_bf16_f32 v28, v28, v29
	v_cvt_pk_bf16_f32 v29, v30, v31
	v_add_u32_e32 v44, 0x90, v152
	v_ashrrev_i32_e32 v45, 31, v44
	v_lshl_add_u64 v[46:47], v[120:121], 0, v[44:45]
	v_cvt_pk_bf16_f32 v30, v24, v25
	v_lshl_add_u64 v[24:25], v[122:123], 0, v[44:45]
	v_lshlrev_b64 v[46:47], 9, v[46:47]
	v_lshlrev_b64 v[24:25], 9, v[24:25]
	v_lshl_add_u64 v[46:47], s[0:1], 0, v[46:47]
	v_lshl_add_u64 v[24:25], s[0:1], 0, v[24:25]
	v_cvt_pk_bf16_f32 v40, v52, v53
	v_cvt_pk_bf16_f32 v41, v54, v55
	v_cvt_pk_bf16_f32 v42, v48, v49
	v_cvt_pk_bf16_f32 v43, v50, v51
	v_lshl_add_u64 v[46:47], v[46:47], 0, v[136:137]
	v_cvt_pk_bf16_f32 v31, v26, v27
	v_lshl_add_u64 v[24:25], v[24:25], 0, v[124:125]
	global_store_dwordx4 v[46:47], v[40:43], off sc1
	global_store_dwordx4 v[24:25], v[28:31], off sc1
	v_cvt_pk_bf16_f32 v12, v12, v13
	v_cvt_pk_bf16_f32 v13, v14, v15
	v_add_u32_e32 v28, 0xa0, v152
	v_ashrrev_i32_e32 v29, 31, v28
	v_lshl_add_u64 v[30:31], v[120:121], 0, v[28:29]
	v_cvt_pk_bf16_f32 v14, v8, v9
	v_lshl_add_u64 v[8:9], v[122:123], 0, v[28:29]
	v_lshlrev_b64 v[30:31], 9, v[30:31]
	v_lshlrev_b64 v[8:9], 9, v[8:9]
	v_lshl_add_u64 v[30:31], s[0:1], 0, v[30:31]
	v_lshl_add_u64 v[8:9], s[0:1], 0, v[8:9]
	v_cvt_pk_bf16_f32 v24, v36, v37
	v_cvt_pk_bf16_f32 v25, v38, v39
	v_cvt_pk_bf16_f32 v26, v32, v33
	v_cvt_pk_bf16_f32 v27, v34, v35
	v_lshl_add_u64 v[30:31], v[30:31], 0, v[136:137]
	v_cvt_pk_bf16_f32 v15, v10, v11
	v_lshl_add_u64 v[8:9], v[8:9], 0, v[124:125]
	global_store_dwordx4 v[30:31], v[24:27], off sc1
	global_store_dwordx4 v[8:9], v[12:15], off sc1
	v_cvt_pk_bf16_f32 v4, v4, v5
	v_cvt_pk_bf16_f32 v5, v6, v7
	v_add_u32_e32 v12, 0xb0, v152
	v_ashrrev_i32_e32 v13, 31, v12
	v_lshl_add_u64 v[14:15], v[120:121], 0, v[12:13]
	v_cvt_pk_bf16_f32 v6, v0, v1
	v_lshl_add_u64 v[0:1], v[122:123], 0, v[12:13]
	v_lshlrev_b64 v[14:15], 9, v[14:15]
	v_lshlrev_b64 v[0:1], 9, v[0:1]
	v_lshl_add_u64 v[14:15], s[0:1], 0, v[14:15]
	v_lshl_add_u64 v[0:1], s[0:1], 0, v[0:1]
	v_cvt_pk_bf16_f32 v8, v20, v21
	v_cvt_pk_bf16_f32 v9, v22, v23
	v_cvt_pk_bf16_f32 v10, v16, v17
	v_cvt_pk_bf16_f32 v11, v18, v19
	v_lshl_add_u64 v[14:15], v[14:15], 0, v[136:137]
	v_cvt_pk_bf16_f32 v7, v2, v3
	v_lshl_add_u64 v[0:1], v[0:1], 0, v[124:125]
	s_and_b64 vcc, exec, s[2:3]
	s_mov_b32 s50, s6
	s_mov_b32 s12, s10
	s_mov_b64 s[20:21], s[16:17]
	s_mov_b64 s[18:19], s[14:15]
	global_store_dwordx4 v[14:15], v[8:11], off sc1
	global_store_dwordx4 v[0:1], v[4:7], off sc1
	s_cbranch_vccz .LBB0_490
	s_waitcnt vmcnt(0)
	s_cmpk_gt_u32 s25, 0xff
	s_cbranch_scc1 .LBB0_501
	s_barrier

.LBB0_721:
	v_readlane_b32 s2, v254, 10
	v_mov_b32_e32 v33, 0
	v_mov_b32_e32 v0, 0
	s_cmpk_gt_i32 s2, 0xff
	s_waitcnt lgkmcnt(0)
	s_barrier
	v_readlane_b32 s3, v254, 11
	s_cbranch_scc1 .LBB0_734
	s_bitcmp1_b32 s2, 0
	s_cbranch_scc1 .Lp6_dummy
	v_mbcnt_lo_u32_b32 v0, -1, v0
	v_mbcnt_hi_u32_b32 v6, -1, v0
	v_readlane_b32 s2, v254, 7
	v_and_b32_e32 v3, 63, v6
	v_lshlrev_b32_e32 v3, 2, v3
	v_add_u32_e32 v2, s2, v6
	v_ashrrev_i32_e32 v7, 6, v2
	v_lshlrev_b32_e32 v4, 12, v7
	v_add3_u32 v63, s91, v4, v3
	v_lshlrev_b32_e32 v4, 10, v7
	v_and_b32_e32 v2, 0xffffffc0, v2
	v_add3_u32 v64, s91, v4, v3
	v_ashrrev_i32_e32 v3, 31, v2
	v_lshlrev_b64 v[2:3], 1, v[2:3]
	v_lshrrev_b32_e32 v8, 1, v6
	v_lshl_add_u64 v[4:5], s[16:17], 0, v[2:3]
	v_and_b32_e32 v32, 16, v8
	v_lshl_add_u64 v[2:3], s[14:15], 0, v[2:3]
	v_lshl_add_u64 v[36:37], v[2:3], 0, v[32:33]
	v_lshrrev_b32_e32 v2, 3, v6
	v_and_b32_e32 v2, 4, v2
	v_lshl_or_b32 v65, v7, 3, v2
	v_mbcnt_lo_u32_b32 v2, -1, 0
	v_mbcnt_hi_u32_b32 v2, -1, v2
	v_and_b32_e32 v3, 64, v2
	v_lshl_add_u64 v[34:35], v[4:5], 0, v[32:33]
	v_add_u32_e32 v3, 64, v3
	v_xor_b32_e32 v4, 16, v2
	v_cmp_lt_i32_e64 s[2:3], v4, v3
	v_lshlrev_b32_e32 v0, 8, v7
	v_ashrrev_i32_e32 v1, 31, v0
	v_cndmask_b32_e64 v4, v2, v4, s[2:3]
	v_lshlrev_b32_e32 v66, 2, v4
	v_xor_b32_e32 v4, 8, v2
	v_cmp_lt_i32_e64 s[2:3], v4, v3
	v_lshlrev_b64 v[0:1], 1, v[0:1]
	v_or_b32_e32 v0, v0, v32
	v_cndmask_b32_e64 v4, v2, v4, s[2:3]
	v_lshlrev_b32_e32 v67, 2, v4
	v_xor_b32_e32 v4, 4, v2
	v_cmp_lt_i32_e64 s[2:3], v4, v3
	v_lshl_add_u64 v[0:1], s[0:1], 0, v[0:1]
	v_readlane_b32 s7, v254, 0
	v_cndmask_b32_e64 v4, v2, v4, s[2:3]
	v_lshlrev_b32_e32 v68, 2, v4
	v_xor_b32_e32 v4, 2, v2
	v_cmp_lt_i32_e64 s[2:3], v4, v3
	v_readlane_b32 s14, v254, 14
	v_and_b32_e32 v62, 31, v6
	v_cndmask_b32_e64 v4, v2, v4, s[2:3]
	v_lshlrev_b32_e32 v69, 2, v4
	v_xor_b32_e32 v4, 1, v2
	v_cmp_lt_i32_e64 s[2:3], v4, v3
	v_cmp_eq_u32_e32 vcc, 0, v62
	v_or_b32_e32 v71, 0x4000, v62
	v_cndmask_b32_e64 v2, v2, v4, s[2:3]
	s_mov_b64 s[2:3], 0x2100080
	v_lshl_add_u64 v[38:39], v[0:1], 0, s[2:3]
	s_lshl_b32 s2, s7, 3
	s_lshl_b32 s3, s14, 3
	s_add_i32 s12, s2, s3
	v_readlane_b32 s2, v254, 15
	v_readlane_b32 s3, v254, 16
	s_load_dword s6, s[2:3], 0xb8
	s_mov_b64 s[2:3], 0x117e0080
	v_lshl_add_u64 v[40:41], v[0:1], 0, s[2:3]
	s_lshl_b32 s2, s7, 5
	s_lshl_b32 s3, s14, 5
	s_waitcnt lgkmcnt(0)
	s_lshl_b32 s13, s6, 4
	s_lshl_b32 s15, s6, 6
	v_readlane_b32 s6, v254, 10
	s_lshr_b32 s6, s6, 1
	v_lshlrev_b32_e32 v70, 2, v2
	s_add_i32 s14, s2, s3
	s_mov_b64 s[2:3], 0x100
	s_mov_b32 s16, s6
	v_readlane_b32 s7, v254, 11
	s_branch .LBB0_724

.Lp6_dummy:
	s_barrier
	s_barrier
	s_barrier
	s_barrier

.LBB0_2128:
	ds_read_b128 v[152:155], v147
	ds_read_b128 v[156:159], v147 offset:1024
	ds_read_b128 v[160:163], v147 offset:2048
	ds_read_b128 v[164:167], v147 offset:3072
	s_add_u32 s20, s18, 0xfff80080
	s_addc_u32 s21, s19, -1
	s_cmp_eq_u32 s55, 28
	s_cselect_b32 s23, s11, s21
	s_cselect_b32 s22, s51, s20
	s_cselect_b32 s21, s9, s54
	s_cselect_b32 s20, s52, s53
	v_lshl_add_u64 v[200:201], s[18:19], 0, v[138:139]
	s_add_i32 m0, s33, 0xc000
	ds_read_b128 v[168:171], v148
	ds_read_b128 v[172:175], v148 offset:1024
	ds_read_b128 v[176:179], v148 offset:2048
	ds_read_b128 v[180:183], v148 offset:3072
	ds_read_b128 v[184:187], v148 offset:4096
	ds_read_b128 v[188:191], v148 offset:5120
	ds_read_b128 v[192:195], v148 offset:6144
	ds_read_b128 v[196:199], v148 offset:7168
	global_load_lds_dwordx4 v[200:201], off
	v_lshl_add_u64 v[200:201], s[18:19], 0, v[140:141]
	s_add_i32 m0, s33, 0xe000
	s_nop 0
	global_load_lds_dwordx4 v[200:201], off
	s_waitcnt lgkmcnt(8)
	s_barrier
	s_waitcnt lgkmcnt(0)
	s_setprio 1
	s_waitcnt lgkmcnt(0)
	v_mfma_f32_16x16x32_bf16 v[124:127], v[152:155], v[168:171], v[124:127]
	v_mfma_f32_16x16x32_bf16 v[120:123], v[160:163], v[168:171], v[120:123]
	v_mfma_f32_16x16x32_bf16 v[112:115], v[152:155], v[176:179], v[112:115]
	v_mfma_f32_16x16x32_bf16 v[104:107], v[160:163], v[176:179], v[104:107]
	v_mfma_f32_16x16x32_bf16 v[100:103], v[152:155], v[184:187], v[100:103]
	v_mfma_f32_16x16x32_bf16 v[96:99], v[160:163], v[184:187], v[96:99]
	v_mfma_f32_16x16x32_bf16 v[84:87], v[152:155], v[192:195], v[84:87]
	v_mfma_f32_16x16x32_bf16 v[80:83], v[160:163], v[192:195], v[80:83]
	v_mfma_f32_16x16x32_bf16 v[124:127], v[156:159], v[172:175], v[124:127]
	v_mfma_f32_16x16x32_bf16 v[120:123], v[164:167], v[172:175], v[120:123]
	v_mfma_f32_16x16x32_bf16 v[112:115], v[156:159], v[180:183], v[112:115]
	v_mfma_f32_16x16x32_bf16 v[104:107], v[164:167], v[180:183], v[104:107]
	v_mfma_f32_16x16x32_bf16 v[100:103], v[156:159], v[188:191], v[100:103]
	v_mfma_f32_16x16x32_bf16 v[96:99], v[164:167], v[188:191], v[96:99]
	v_mfma_f32_16x16x32_bf16 v[84:87], v[156:159], v[196:199], v[84:87]
	v_mfma_f32_16x16x32_bf16 v[80:83], v[164:167], v[196:199], v[80:83]
	s_setprio 0
	s_barrier
	s_mov_b32 m0, s13
	v_lshl_add_u64 v[216:217], s[20:21], 0, v[130:131]
	ds_read_b128 v[200:203], v149
	ds_read_b128 v[204:207], v149 offset:1024
	ds_read_b128 v[208:211], v149 offset:2048
	ds_read_b128 v[212:215], v149 offset:3072
	global_load_lds_dwordx4 v[216:217], off
	v_lshl_add_u64 v[218:219], s[20:21], 0, v[134:135]
	s_mov_b32 m0, s31
	s_nop 0
	global_load_lds_dwordx4 v[218:219], off
	s_barrier
	s_waitcnt lgkmcnt(0)
	s_setprio 1
	s_waitcnt lgkmcnt(0)
	v_mfma_f32_16x16x32_bf16 v[116:119], v[200:203], v[168:171], v[116:119]
	v_mfma_f32_16x16x32_bf16 v[108:111], v[208:211], v[168:171], v[108:111]
	v_mfma_f32_16x16x32_bf16 v[92:95], v[200:203], v[176:179], v[92:95]
	v_mfma_f32_16x16x32_bf16 v[88:91], v[208:211], v[176:179], v[88:91]
	v_mfma_f32_16x16x32_bf16 v[76:79], v[200:203], v[184:187], v[76:79]
	v_mfma_f32_16x16x32_bf16 v[72:75], v[208:211], v[184:187], v[72:75]
	v_mfma_f32_16x16x32_bf16 v[68:71], v[200:203], v[192:195], v[68:71]
	v_mfma_f32_16x16x32_bf16 v[64:67], v[208:211], v[192:195], v[64:67]
	v_mfma_f32_16x16x32_bf16 v[116:119], v[204:207], v[172:175], v[116:119]
	v_mfma_f32_16x16x32_bf16 v[108:111], v[212:215], v[172:175], v[108:111]
	v_mfma_f32_16x16x32_bf16 v[92:95], v[204:207], v[180:183], v[92:95]
	v_mfma_f32_16x16x32_bf16 v[88:91], v[212:215], v[180:183], v[88:91]
	v_mfma_f32_16x16x32_bf16 v[76:79], v[204:207], v[188:191], v[76:79]
	v_mfma_f32_16x16x32_bf16 v[72:75], v[212:215], v[188:191], v[72:75]
	v_mfma_f32_16x16x32_bf16 v[68:71], v[204:207], v[196:199], v[68:71]
	v_mfma_f32_16x16x32_bf16 v[64:67], v[212:215], v[196:199], v[64:67]
	s_setprio 0
	s_mov_b32 m0, s33
	v_lshl_add_u64 v[220:221], s[22:23], 0, v[128:129]
	s_barrier
	ds_read_b128 v[168:171], v148 offset:16384
	ds_read_b128 v[172:175], v148 offset:17408
	ds_read_b128 v[176:179], v148 offset:18432
	ds_read_b128 v[180:183], v148 offset:19456
	ds_read_b128 v[184:187], v148 offset:20480
	ds_read_b128 v[188:191], v148 offset:21504
	ds_read_b128 v[192:195], v148 offset:22528
	ds_read_b128 v[196:199], v148 offset:23552
	global_load_lds_dwordx4 v[220:221], off
	v_lshl_add_u64 v[222:223], s[22:23], 0, v[132:133]
	s_mov_b32 m0, s34
	s_nop 0
	global_load_lds_dwordx4 v[222:223], off
	s_barrier
	s_waitcnt lgkmcnt(0)
	s_setprio 1
	s_waitcnt lgkmcnt(0)
	v_mfma_f32_16x16x32_bf16 v[60:63], v[152:155], v[168:171], v[60:63]
	v_mfma_f32_16x16x32_bf16 v[56:59], v[160:163], v[168:171], v[56:59]
	v_mfma_f32_16x16x32_bf16 v[52:55], v[152:155], v[176:179], v[52:55]
	v_mfma_f32_16x16x32_bf16 v[48:51], v[160:163], v[176:179], v[48:51]
	v_mfma_f32_16x16x32_bf16 v[36:39], v[152:155], v[184:187], v[36:39]
	v_mfma_f32_16x16x32_bf16 v[32:35], v[160:163], v[184:187], v[32:35]
	v_mfma_f32_16x16x32_bf16 v[20:23], v[152:155], v[192:195], v[20:23]
	v_mfma_f32_16x16x32_bf16 v[16:19], v[160:163], v[192:195], v[16:19]
	v_mfma_f32_16x16x32_bf16 v[60:63], v[156:159], v[172:175], v[60:63]
	v_mfma_f32_16x16x32_bf16 v[56:59], v[164:167], v[172:175], v[56:59]
	v_mfma_f32_16x16x32_bf16 v[52:55], v[156:159], v[180:183], v[52:55]
	v_mfma_f32_16x16x32_bf16 v[48:51], v[164:167], v[180:183], v[48:51]
	v_mfma_f32_16x16x32_bf16 v[36:39], v[156:159], v[188:191], v[36:39]
	v_mfma_f32_16x16x32_bf16 v[32:35], v[164:167], v[188:191], v[32:35]
	v_mfma_f32_16x16x32_bf16 v[20:23], v[156:159], v[196:199], v[20:23]
	v_mfma_f32_16x16x32_bf16 v[16:19], v[164:167], v[196:199], v[16:19]
	s_setprio 0
	s_barrier
	s_add_u32 s56, s20, 0x80000
	s_addc_u32 s57, s21, 0
	s_mov_b32 m0, s35
	v_lshl_add_u64 v[152:153], s[56:57], 0, v[130:131]
	global_load_lds_dwordx4 v[152:153], off
	v_lshl_add_u64 v[152:153], s[56:57], 0, v[134:135]
	s_mov_b32 m0, s36
	s_nop 0
	global_load_lds_dwordx4 v[152:153], off
	s_waitcnt vmcnt(6)
	s_barrier
	s_setprio 1
	v_mfma_f32_16x16x32_bf16 v[44:47], v[200:203], v[168:171], v[44:47]
	v_mfma_f32_16x16x32_bf16 v[40:43], v[208:211], v[168:171], v[40:43]
	v_mfma_f32_16x16x32_bf16 v[28:31], v[200:203], v[176:179], v[28:31]
	v_mfma_f32_16x16x32_bf16 v[24:27], v[208:211], v[176:179], v[24:27]
	v_mfma_f32_16x16x32_bf16 v[12:15], v[200:203], v[184:187], v[12:15]
	v_mfma_f32_16x16x32_bf16 v[8:11], v[208:211], v[184:187], v[8:11]
	v_mfma_f32_16x16x32_bf16 v[4:7], v[200:203], v[192:195], v[4:7]
	v_mfma_f32_16x16x32_bf16 v[0:3], v[208:211], v[192:195], v[0:3]
	v_mfma_f32_16x16x32_bf16 v[44:47], v[204:207], v[172:175], v[44:47]
	v_mfma_f32_16x16x32_bf16 v[40:43], v[212:215], v[172:175], v[40:43]
	v_mfma_f32_16x16x32_bf16 v[28:31], v[204:207], v[180:183], v[28:31]
	v_mfma_f32_16x16x32_bf16 v[24:27], v[212:215], v[180:183], v[24:27]
	v_mfma_f32_16x16x32_bf16 v[12:15], v[204:207], v[188:191], v[12:15]
	v_mfma_f32_16x16x32_bf16 v[8:11], v[212:215], v[188:191], v[8:11]
	v_mfma_f32_16x16x32_bf16 v[4:7], v[204:207], v[196:199], v[4:7]
	v_mfma_f32_16x16x32_bf16 v[0:3], v[212:215], v[196:199], v[0:3]
	s_setprio 0
	s_barrier
	ds_read_b128 v[152:155], v150
	ds_read_b128 v[156:159], v150 offset:1024
	ds_read_b128 v[160:163], v150 offset:2048
	ds_read_b128 v[164:167], v150 offset:3072
	s_add_u32 s22, s22, 0x80000
	s_addc_u32 s23, s23, 0
	s_mov_b32 m0, s37
	v_lshl_add_u64 v[200:201], s[22:23], 0, v[128:129]
	ds_read_b128 v[168:171], v148 offset:32768
	ds_read_b128 v[172:175], v148 offset:33792
	ds_read_b128 v[176:179], v148 offset:34816
	ds_read_b128 v[180:183], v148 offset:35840
	ds_read_b128 v[184:187], v148 offset:36864
	ds_read_b128 v[188:191], v148 offset:37888
	ds_read_b128 v[192:195], v148 offset:38912
	ds_read_b128 v[196:199], v148 offset:39936
	global_load_lds_dwordx4 v[200:201], off
	v_lshl_add_u64 v[200:201], s[22:23], 0, v[132:133]
	s_mov_b32 m0, s38
	s_nop 0
	global_load_lds_dwordx4 v[200:201], off
	s_waitcnt lgkmcnt(8)
	s_barrier
	s_waitcnt lgkmcnt(0)
	s_setprio 1
	s_waitcnt lgkmcnt(0)
	v_mfma_f32_16x16x32_bf16 v[124:127], v[152:155], v[168:171], v[124:127]
	v_mfma_f32_16x16x32_bf16 v[120:123], v[160:163], v[168:171], v[120:123]
	v_mfma_f32_16x16x32_bf16 v[112:115], v[152:155], v[176:179], v[112:115]
	v_mfma_f32_16x16x32_bf16 v[104:107], v[160:163], v[176:179], v[104:107]
	v_mfma_f32_16x16x32_bf16 v[100:103], v[152:155], v[184:187], v[100:103]
	v_mfma_f32_16x16x32_bf16 v[96:99], v[160:163], v[184:187], v[96:99]
	v_mfma_f32_16x16x32_bf16 v[84:87], v[152:155], v[192:195], v[84:87]
	v_mfma_f32_16x16x32_bf16 v[80:83], v[160:163], v[192:195], v[80:83]
	v_mfma_f32_16x16x32_bf16 v[124:127], v[156:159], v[172:175], v[124:127]
	v_mfma_f32_16x16x32_bf16 v[120:123], v[164:167], v[172:175], v[120:123]
	v_mfma_f32_16x16x32_bf16 v[112:115], v[156:159], v[180:183], v[112:115]
	v_mfma_f32_16x16x32_bf16 v[104:107], v[164:167], v[180:183], v[104:107]
	v_mfma_f32_16x16x32_bf16 v[100:103], v[156:159], v[188:191], v[100:103]
	v_mfma_f32_16x16x32_bf16 v[96:99], v[164:167], v[188:191], v[96:99]
	v_mfma_f32_16x16x32_bf16 v[84:87], v[156:159], v[196:199], v[84:87]
	v_mfma_f32_16x16x32_bf16 v[80:83], v[164:167], v[196:199], v[80:83]
	s_setprio 0
	s_barrier
	s_mov_b32 m0, s42
	v_lshl_add_u64 v[216:217], v[216:217], 0, s[6:7]
	ds_read_b128 v[200:203], v151
	ds_read_b128 v[204:207], v151 offset:1024
	ds_read_b128 v[208:211], v151 offset:2048
	ds_read_b128 v[212:215], v151 offset:3072
	global_load_lds_dwordx4 v[216:217], off
	v_lshl_add_u64 v[216:217], v[218:219], 0, s[6:7]
	s_mov_b32 m0, s43
	s_nop 0
	global_load_lds_dwordx4 v[216:217], off
	s_barrier
	s_waitcnt lgkmcnt(0)
	s_setprio 1
	s_waitcnt lgkmcnt(0)
	v_mfma_f32_16x16x32_bf16 v[116:119], v[200:203], v[168:171], v[116:119]
	v_mfma_f32_16x16x32_bf16 v[108:111], v[208:211], v[168:171], v[108:111]
	v_mfma_f32_16x16x32_bf16 v[92:95], v[200:203], v[176:179], v[92:95]
	v_mfma_f32_16x16x32_bf16 v[88:91], v[208:211], v[176:179], v[88:91]
	v_mfma_f32_16x16x32_bf16 v[76:79], v[200:203], v[184:187], v[76:79]
	v_mfma_f32_16x16x32_bf16 v[72:75], v[208:211], v[184:187], v[72:75]
	v_mfma_f32_16x16x32_bf16 v[68:71], v[200:203], v[192:195], v[68:71]
	v_mfma_f32_16x16x32_bf16 v[64:67], v[208:211], v[192:195], v[64:67]
	v_mfma_f32_16x16x32_bf16 v[116:119], v[204:207], v[172:175], v[116:119]
	v_mfma_f32_16x16x32_bf16 v[108:111], v[212:215], v[172:175], v[108:111]
	v_mfma_f32_16x16x32_bf16 v[92:95], v[204:207], v[180:183], v[92:95]
	v_mfma_f32_16x16x32_bf16 v[88:91], v[212:215], v[180:183], v[88:91]
	v_mfma_f32_16x16x32_bf16 v[76:79], v[204:207], v[188:191], v[76:79]
	v_mfma_f32_16x16x32_bf16 v[72:75], v[212:215], v[188:191], v[72:75]
	v_mfma_f32_16x16x32_bf16 v[68:71], v[204:207], v[196:199], v[68:71]
	v_mfma_f32_16x16x32_bf16 v[64:67], v[212:215], v[196:199], v[64:67]
	s_setprio 0
	s_mov_b32 m0, s44
	v_lshl_add_u64 v[216:217], v[220:221], 0, s[6:7]
	s_barrier
	ds_read_b128 v[168:171], v148 offset:49152
	ds_read_b128 v[172:175], v148 offset:50176
	ds_read_b128 v[176:179], v148 offset:51200
	ds_read_b128 v[180:183], v148 offset:52224
	ds_read_b128 v[184:187], v148 offset:53248
	ds_read_b128 v[188:191], v148 offset:54272
	ds_read_b128 v[192:195], v148 offset:55296
	ds_read_b128 v[196:199], v148 offset:56320
	global_load_lds_dwordx4 v[216:217], off
	v_lshl_add_u64 v[216:217], v[222:223], 0, s[6:7]
	s_mov_b32 m0, s45
	s_nop 0
	global_load_lds_dwordx4 v[216:217], off
	s_barrier
	s_waitcnt lgkmcnt(0)
	s_setprio 1
	s_waitcnt lgkmcnt(0)
	v_mfma_f32_16x16x32_bf16 v[60:63], v[152:155], v[168:171], v[60:63]
	v_mfma_f32_16x16x32_bf16 v[56:59], v[160:163], v[168:171], v[56:59]
	v_mfma_f32_16x16x32_bf16 v[52:55], v[152:155], v[176:179], v[52:55]
	v_mfma_f32_16x16x32_bf16 v[48:51], v[160:163], v[176:179], v[48:51]
	v_mfma_f32_16x16x32_bf16 v[36:39], v[152:155], v[184:187], v[36:39]
	v_mfma_f32_16x16x32_bf16 v[32:35], v[160:163], v[184:187], v[32:35]
	v_mfma_f32_16x16x32_bf16 v[20:23], v[152:155], v[192:195], v[20:23]
	v_mfma_f32_16x16x32_bf16 v[16:19], v[160:163], v[192:195], v[16:19]
	v_mfma_f32_16x16x32_bf16 v[60:63], v[156:159], v[172:175], v[60:63]
	v_mfma_f32_16x16x32_bf16 v[56:59], v[164:167], v[172:175], v[56:59]
	v_mfma_f32_16x16x32_bf16 v[52:55], v[156:159], v[180:183], v[52:55]
	v_mfma_f32_16x16x32_bf16 v[48:51], v[164:167], v[180:183], v[48:51]
	v_mfma_f32_16x16x32_bf16 v[36:39], v[156:159], v[188:191], v[36:39]
	v_mfma_f32_16x16x32_bf16 v[32:35], v[164:167], v[188:191], v[32:35]
	v_mfma_f32_16x16x32_bf16 v[20:23], v[156:159], v[196:199], v[20:23]
	v_mfma_f32_16x16x32_bf16 v[16:19], v[164:167], v[196:199], v[16:19]
	s_setprio 0
	s_barrier
	s_add_u32 s20, s20, 0x80080
	s_addc_u32 s21, s21, 0
	s_mov_b32 m0, s46
	v_lshl_add_u64 v[152:153], s[20:21], 0, v[130:131]
	global_load_lds_dwordx4 v[152:153], off
	v_lshl_add_u64 v[152:153], s[20:21], 0, v[134:135]
	s_mov_b32 m0, s47
	s_nop 0
	global_load_lds_dwordx4 v[152:153], off
	s_waitcnt vmcnt(6)
	s_barrier
	s_setprio 1
	v_mfma_f32_16x16x32_bf16 v[44:47], v[200:203], v[168:171], v[44:47]
	v_mfma_f32_16x16x32_bf16 v[40:43], v[208:211], v[168:171], v[40:43]
	v_mfma_f32_16x16x32_bf16 v[28:31], v[200:203], v[176:179], v[28:31]
	v_mfma_f32_16x16x32_bf16 v[24:27], v[208:211], v[176:179], v[24:27]
	v_mfma_f32_16x16x32_bf16 v[12:15], v[200:203], v[184:187], v[12:15]
	v_mfma_f32_16x16x32_bf16 v[8:11], v[208:211], v[184:187], v[8:11]
	v_mfma_f32_16x16x32_bf16 v[4:7], v[200:203], v[192:195], v[4:7]
	v_mfma_f32_16x16x32_bf16 v[0:3], v[208:211], v[192:195], v[0:3]
	v_mfma_f32_16x16x32_bf16 v[44:47], v[204:207], v[172:175], v[44:47]
	v_mfma_f32_16x16x32_bf16 v[40:43], v[212:215], v[172:175], v[40:43]
	v_mfma_f32_16x16x32_bf16 v[28:31], v[204:207], v[180:183], v[28:31]
	v_mfma_f32_16x16x32_bf16 v[24:27], v[212:215], v[180:183], v[24:27]
	v_mfma_f32_16x16x32_bf16 v[12:15], v[204:207], v[188:191], v[12:15]
	v_mfma_f32_16x16x32_bf16 v[8:11], v[212:215], v[188:191], v[8:11]
	v_mfma_f32_16x16x32_bf16 v[4:7], v[204:207], v[196:199], v[4:7]
	v_mfma_f32_16x16x32_bf16 v[0:3], v[212:215], v[196:199], v[0:3]
	s_setprio 0
	s_add_i32 s55, s55, 2
	s_add_u32 s18, s18, 0x100
	s_addc_u32 s19, s19, 0
	s_add_u32 s53, s53, 0x100
	s_addc_u32 s54, s54, 0
	s_cmp_gt_u32 s55, 29
	s_barrier
	s_cbranch_scc0 .LBB0_2128
	v_mov_b32_e32 v136, 0
	s_lshl_b32 s9, s12, 8
	v_mbcnt_lo_u32_b32 v136, -1, v136
	v_mbcnt_hi_u32_b32 v136, -1, v136
	s_add_i32 s9, s9, s40
	v_and_or_b32 v152, v136, 15, s9
	s_lshl_b32 s9, s50, 8
	v_ashrrev_i32_e32 v136, 1, v136
	v_and_b32_e32 v136, -8, v136
	s_or_b32 s9, s9, s41
	v_add_u32_e32 v154, s9, v136
	v_cvt_pk_bf16_f32 v124, v124, v125
	v_cvt_pk_bf16_f32 v125, v126, v127
	v_cvt_pk_bf16_f32 v126, v120, v121
	v_lshrrev_b32_e32 v120, 8, v154
	v_ashrrev_i32_e32 v153, 31, v152
	v_mul_hi_i32_i24_e32 v121, 0x4080, v120
	v_mul_i32_i24_e32 v120, 0x4080, v120
	v_cvt_pk_bf16_f32 v127, v122, v123
	v_lshl_add_u64 v[122:123], v[120:121], 0, v[152:153]
	v_and_b32_e32 v136, 0xf8, v154
	v_lshlrev_b64 v[122:123], 9, v[122:123]
	v_lshl_add_u64 v[122:123], s[4:5], 0, v[122:123]
	v_lshlrev_b32_e32 v136, 1, v136
	v_lshl_add_u64 v[122:123], v[122:123], 0, v[136:137]
	global_store_dwordx4 v[122:123], v[124:127], off sc1
	v_cvt_pk_bf16_f32 v116, v116, v117
	v_cvt_pk_bf16_f32 v117, v118, v119
	v_add_u32_e32 v124, 0x80, v154
	v_cvt_pk_bf16_f32 v118, v108, v109
	v_lshrrev_b32_e32 v108, 8, v124
	v_mul_hi_i32_i24_e32 v123, 0x4080, v108
	v_mul_i32_i24_e32 v122, 0x4080, v108
	v_lshl_add_u64 v[108:109], v[122:123], 0, v[152:153]
	v_cvt_pk_bf16_f32 v119, v110, v111
	v_and_b32_e32 v110, 0xf8, v124
	v_lshlrev_b64 v[108:109], 9, v[108:109]
	v_lshl_add_u64 v[108:109], s[4:5], 0, v[108:109]
	v_lshlrev_b32_e32 v124, 1, v110
	v_mov_b32_e32 v125, v137
	v_lshl_add_u64 v[108:109], v[108:109], 0, v[124:125]
	global_store_dwordx4 v[108:109], v[116:119], off sc1
	v_cvt_pk_bf16_f32 v110, v104, v105
	v_cvt_pk_bf16_f32 v92, v92, v93
	v_or_b32_e32 v116, 16, v152
	v_ashrrev_i32_e32 v117, 31, v116
	v_lshl_add_u64 v[104:105], v[120:121], 0, v[116:117]
	v_cvt_pk_bf16_f32 v93, v94, v95
	v_cvt_pk_bf16_f32 v94, v88, v89
	v_lshl_add_u64 v[88:89], v[122:123], 0, v[116:117]
	v_lshlrev_b64 v[104:105], 9, v[104:105]
	v_lshlrev_b64 v[88:89], 9, v[88:89]
	v_lshl_add_u64 v[104:105], s[4:5], 0, v[104:105]
	v_lshl_add_u64 v[88:89], s[4:5], 0, v[88:89]
	v_cvt_pk_bf16_f32 v108, v112, v113
	v_cvt_pk_bf16_f32 v109, v114, v115
	v_cvt_pk_bf16_f32 v111, v106, v107
	v_lshl_add_u64 v[104:105], v[104:105], 0, v[136:137]
	v_cvt_pk_bf16_f32 v95, v90, v91
	v_lshl_add_u64 v[88:89], v[88:89], 0, v[124:125]
	global_store_dwordx4 v[104:105], v[108:111], off sc1
	global_store_dwordx4 v[88:89], v[92:95], off sc1
	v_cvt_pk_bf16_f32 v76, v76, v77
	v_cvt_pk_bf16_f32 v77, v78, v79
	v_or_b32_e32 v92, 32, v152
	v_ashrrev_i32_e32 v93, 31, v92
	v_lshl_add_u64 v[94:95], v[120:121], 0, v[92:93]
	v_cvt_pk_bf16_f32 v78, v72, v73
	v_lshl_add_u64 v[72:73], v[122:123], 0, v[92:93]
	v_lshlrev_b64 v[94:95], 9, v[94:95]
	v_lshlrev_b64 v[72:73], 9, v[72:73]
	v_lshl_add_u64 v[94:95], s[4:5], 0, v[94:95]
	v_lshl_add_u64 v[72:73], s[4:5], 0, v[72:73]
	v_cvt_pk_bf16_f32 v88, v100, v101
	v_cvt_pk_bf16_f32 v89, v102, v103
	v_cvt_pk_bf16_f32 v90, v96, v97
	v_cvt_pk_bf16_f32 v91, v98, v99
	v_lshl_add_u64 v[94:95], v[94:95], 0, v[136:137]
	v_cvt_pk_bf16_f32 v79, v74, v75
	v_lshl_add_u64 v[72:73], v[72:73], 0, v[124:125]
	global_store_dwordx4 v[94:95], v[88:91], off sc1
	global_store_dwordx4 v[72:73], v[76:79], off sc1
	v_cvt_pk_bf16_f32 v68, v68, v69
	v_cvt_pk_bf16_f32 v69, v70, v71
	v_or_b32_e32 v76, 48, v152
	v_ashrrev_i32_e32 v77, 31, v76
	v_lshl_add_u64 v[78:79], v[120:121], 0, v[76:77]
	v_cvt_pk_bf16_f32 v70, v64, v65
	v_lshl_add_u64 v[64:65], v[122:123], 0, v[76:77]
	v_lshlrev_b64 v[78:79], 9, v[78:79]
	v_lshlrev_b64 v[64:65], 9, v[64:65]
	v_lshl_add_u64 v[78:79], s[4:5], 0, v[78:79]
	v_lshl_add_u64 v[64:65], s[4:5], 0, v[64:65]
	v_cvt_pk_bf16_f32 v72, v84, v85
	v_cvt_pk_bf16_f32 v73, v86, v87
	v_cvt_pk_bf16_f32 v74, v80, v81
	v_cvt_pk_bf16_f32 v75, v82, v83
	v_lshl_add_u64 v[78:79], v[78:79], 0, v[136:137]
	v_cvt_pk_bf16_f32 v71, v66, v67
	v_lshl_add_u64 v[64:65], v[64:65], 0, v[124:125]
	global_store_dwordx4 v[78:79], v[72:75], off sc1
	global_store_dwordx4 v[64:65], v[68:71], off sc1
	v_add_u32_e32 v64, 0x80, v152
	v_ashrrev_i32_e32 v65, 31, v64
	v_cvt_pk_bf16_f32 v60, v60, v61
	v_cvt_pk_bf16_f32 v61, v62, v63
	v_cvt_pk_bf16_f32 v62, v56, v57
	v_lshl_add_u64 v[56:57], v[120:121], 0, v[64:65]
	v_cvt_pk_bf16_f32 v44, v44, v45
	v_cvt_pk_bf16_f32 v45, v46, v47
	v_cvt_pk_bf16_f32 v46, v40, v41
	v_lshl_add_u64 v[40:41], v[122:123], 0, v[64:65]
	v_lshlrev_b64 v[56:57], 9, v[56:57]
	v_lshlrev_b64 v[40:41], 9, v[40:41]
	v_lshl_add_u64 v[56:57], s[4:5], 0, v[56:57]
	v_lshl_add_u64 v[40:41], s[4:5], 0, v[40:41]
	v_cvt_pk_bf16_f32 v63, v58, v59
	v_lshl_add_u64 v[56:57], v[56:57], 0, v[136:137]
	v_cvt_pk_bf16_f32 v47, v42, v43
	v_lshl_add_u64 v[40:41], v[40:41], 0, v[124:125]
	global_store_dwordx4 v[56:57], v[60:63], off sc1
	global_store_dwordx4 v[40:41], v[44:47], off sc1
	v_cvt_pk_bf16_f32 v28, v28, v29
	v_cvt_pk_bf16_f32 v29, v30, v31
	v_add_u32_e32 v44, 0x90, v152
	v_ashrrev_i32_e32 v45, 31, v44
	v_lshl_add_u64 v[46:47], v[120:121], 0, v[44:45]
	v_cvt_pk_bf16_f32 v30, v24, v25
	v_lshl_add_u64 v[24:25], v[122:123], 0, v[44:45]
	v_lshlrev_b64 v[46:47], 9, v[46:47]
	v_lshlrev_b64 v[24:25], 9, v[24:25]
	v_lshl_add_u64 v[46:47], s[4:5], 0, v[46:47]
	v_lshl_add_u64 v[24:25], s[4:5], 0, v[24:25]
	v_cvt_pk_bf16_f32 v40, v52, v53
	v_cvt_pk_bf16_f32 v41, v54, v55
	v_cvt_pk_bf16_f32 v42, v48, v49
	v_cvt_pk_bf16_f32 v43, v50, v51
	v_lshl_add_u64 v[46:47], v[46:47], 0, v[136:137]
	v_cvt_pk_bf16_f32 v31, v26, v27
	v_lshl_add_u64 v[24:25], v[24:25], 0, v[124:125]
	global_store_dwordx4 v[46:47], v[40:43], off sc1
	global_store_dwordx4 v[24:25], v[28:31], off sc1
	v_cvt_pk_bf16_f32 v12, v12, v13
	v_cvt_pk_bf16_f32 v13, v14, v15
	v_add_u32_e32 v28, 0xa0, v152
	v_ashrrev_i32_e32 v29, 31, v28
	v_lshl_add_u64 v[30:31], v[120:121], 0, v[28:29]
	v_cvt_pk_bf16_f32 v14, v8, v9
	v_lshl_add_u64 v[8:9], v[122:123], 0, v[28:29]
	v_lshlrev_b64 v[30:31], 9, v[30:31]
	v_lshlrev_b64 v[8:9], 9, v[8:9]
	v_lshl_add_u64 v[30:31], s[4:5], 0, v[30:31]
	v_lshl_add_u64 v[8:9], s[4:5], 0, v[8:9]
	v_cvt_pk_bf16_f32 v24, v36, v37
	v_cvt_pk_bf16_f32 v25, v38, v39
	v_cvt_pk_bf16_f32 v26, v32, v33
	v_cvt_pk_bf16_f32 v27, v34, v35
	v_lshl_add_u64 v[30:31], v[30:31], 0, v[136:137]
	v_cvt_pk_bf16_f32 v15, v10, v11
	v_lshl_add_u64 v[8:9], v[8:9], 0, v[124:125]
	global_store_dwordx4 v[30:31], v[24:27], off sc1
	global_store_dwordx4 v[8:9], v[12:15], off sc1
	v_cvt_pk_bf16_f32 v4, v4, v5
	v_cvt_pk_bf16_f32 v5, v6, v7
	v_add_u32_e32 v12, 0xb0, v152
	v_ashrrev_i32_e32 v13, 31, v12
	v_lshl_add_u64 v[14:15], v[120:121], 0, v[12:13]
	v_cvt_pk_bf16_f32 v6, v0, v1
	v_lshl_add_u64 v[0:1], v[122:123], 0, v[12:13]
	v_lshlrev_b64 v[14:15], 9, v[14:15]
	v_lshlrev_b64 v[0:1], 9, v[0:1]
	v_lshl_add_u64 v[14:15], s[4:5], 0, v[14:15]
	v_lshl_add_u64 v[0:1], s[4:5], 0, v[0:1]
	v_cvt_pk_bf16_f32 v8, v20, v21
	v_cvt_pk_bf16_f32 v9, v22, v23
	v_cvt_pk_bf16_f32 v10, v16, v17
	v_cvt_pk_bf16_f32 v11, v18, v19
	v_lshl_add_u64 v[14:15], v[14:15], 0, v[136:137]
	v_cvt_pk_bf16_f32 v7, v2, v3
	v_lshl_add_u64 v[0:1], v[0:1], 0, v[124:125]
	s_and_b64 vcc, exec, s[2:3]
	s_mov_b32 s50, s8
	s_mov_b32 s12, s10
	s_mov_b64 s[20:21], s[16:17]
	s_mov_b64 s[18:19], s[14:15]
	global_store_dwordx4 v[14:15], v[8:11], off sc1
	global_store_dwordx4 v[0:1], v[4:7], off sc1
	s_cbranch_vccz .LBB0_2121
	s_waitcnt vmcnt(0)
	s_cmpk_gt_u32 s25, 0xff
	s_cbranch_scc1 .LBB0_2132
	s_barrier

.LBB0_2133:
	v_readlane_b32 s2, v254, 10
	s_cmpk_gt_i32 s2, 0xff
	s_waitcnt vmcnt(0) lgkmcnt(0)
	s_barrier
	v_readlane_b32 s3, v254, 11
	s_cbranch_scc1 .LBB0_2138
	s_bitcmp1_b32 s2, 0
	s_cbranch_scc1 .Lp9_dummy
	v_mbcnt_lo_u32_b32 v0, -1, v146
	v_mbcnt_hi_u32_b32 v2, -1, v0
	v_readlane_b32 s2, v254, 7
	v_and_b32_e32 v4, 63, v2
	v_lshlrev_b32_e32 v4, 2, v4
	v_add_u32_e32 v0, s2, v2
	v_ashrrev_i32_e32 v3, 6, v0
	v_lshlrev_b32_e32 v0, 9, v3
	v_lshlrev_b32_e32 v5, 12, v3
	v_ashrrev_i32_e32 v1, 31, v0
	v_add3_u32 v43, s91, v5, v4
	v_lshlrev_b32_e32 v5, 10, v3
	v_and_b32_e32 v42, 31, v2
	v_add3_u32 v44, s91, v5, v4
	v_lshrrev_b32_e32 v4, 3, v2
	v_lshrrev_b32_e32 v2, 1, v2
	v_lshlrev_b64 v[0:1], 1, v[0:1]
	v_and_or_b32 v0, v2, 16, v0
	v_lshl_add_u64 v[0:1], s[0:1], 0, v[0:1]
	s_mov_b64 s[2:3], 0x1d00080
	v_readlane_b32 s8, v254, 0
	v_readlane_b32 s10, v254, 14
	v_lshl_add_u64 v[32:33], v[0:1], 0, s[2:3]
	s_lshl_b32 s2, s8, 3
	s_lshl_b32 s3, s10, 3
	s_add_i32 s6, s2, s3
	v_readlane_b32 s2, v254, 15
	v_readlane_b32 s3, v254, 16
	s_load_dword s9, s[2:3], 0xb8
	s_mov_b64 s[2:3], 0x15860080
	v_and_b32_e32 v4, 4, v4
	v_lshl_add_u64 v[34:35], v[0:1], 0, s[2:3]
	s_lshl_b32 s2, s8, 5
	s_lshl_b32 s3, s10, 5
	v_lshl_or_b32 v45, v3, 3, v4
	s_waitcnt lgkmcnt(0)
	s_lshl_b32 s7, s9, 4
	v_or_b32_e32 v46, 0x4000, v42
	s_add_i32 s8, s2, s3
	s_lshl_b32 s9, s9, 6
	v_mov_b32_e32 v37, 0
	s_mov_b64 s[2:3], 0x100
	v_mov_b32_e32 v47, 0x4080
	v_readlane_b32 s10, v254, 10
	s_lshr_b32 s10, s10, 1
	v_readlane_b32 s11, v254, 11

.LBB0_2136:
	global_load_dwordx4 v[48:51], v[40:41], off offset:-128
	global_load_dwordx4 v[52:55], v[38:39], off offset:-128
	global_load_dwordx4 v[56:59], v[40:41], off offset:-96
	global_load_dwordx4 v[60:63], v[38:39], off offset:-96
	global_load_dwordx4 v[64:67], v[40:41], off offset:-64
	s_addk_i32 s11, 0x80
	s_cmpk_lt_u32 s11, 0x1e0
	s_waitcnt vmcnt(3)
	v_mfma_f32_32x32x16_bf16 v[0:15], v[48:51], v[52:55], v[0:15]
	global_load_dwordx4 v[48:51], v[38:39], off offset:-64
	global_load_dwordx4 v[52:55], v[40:41], off offset:-32
	s_waitcnt vmcnt(3)
	v_mfma_f32_32x32x16_bf16 v[16:31], v[56:59], v[60:63], v[16:31]
	global_load_dwordx4 v[56:59], v[38:39], off offset:-32
	global_load_dwordx4 v[60:63], v[40:41], off
	s_waitcnt vmcnt(3)
	v_mfma_f32_32x32x16_bf16 v[0:15], v[64:67], v[48:51], v[0:15]
	global_load_dwordx4 v[48:51], v[38:39], off
	global_load_dwordx4 v[64:67], v[40:41], off offset:32
	s_waitcnt vmcnt(3)
	v_mfma_f32_32x32x16_bf16 v[16:31], v[52:55], v[56:59], v[16:31]
	global_load_dwordx4 v[52:55], v[38:39], off offset:32
	global_load_dwordx4 v[56:59], v[40:41], off offset:64
	global_load_dwordx4 v[68:71], v[40:41], off offset:96
	v_lshl_add_u64 v[40:41], v[40:41], 0, s[2:3]
	s_waitcnt vmcnt(4)
	v_mfma_f32_32x32x16_bf16 v[0:15], v[60:63], v[48:51], v[0:15]
	global_load_dwordx4 v[48:51], v[38:39], off offset:64
	s_waitcnt vmcnt(3)
	v_mfma_f32_32x32x16_bf16 v[16:31], v[64:67], v[52:55], v[16:31]
	global_load_dwordx4 v[52:55], v[38:39], off offset:96
	v_lshl_add_u64 v[38:39], v[38:39], 0, s[2:3]
	s_waitcnt vmcnt(1)
	v_mfma_f32_32x32x16_bf16 v[0:15], v[56:59], v[48:51], v[0:15]
	s_waitcnt vmcnt(0)
	v_mfma_f32_32x32x16_bf16 v[16:31], v[68:71], v[52:55], v[16:31]
	s_cbranch_scc1 .LBB0_2136
	s_nop 10
	v_add_f32_e32 v0, v0, v16
	v_add_f32_e32 v1, v1, v17
	v_add_f32_e32 v2, v2, v18
	v_add_f32_e32 v3, v3, v19
	v_add_f32_e32 v4, v4, v20
	v_add_f32_e32 v5, v5, v21
	v_add_f32_e32 v6, v6, v22
	v_add_f32_e32 v7, v7, v23
	v_add_f32_e32 v8, v8, v24
	v_add_f32_e32 v9, v9, v25
	v_add_f32_e32 v10, v10, v26
	v_add_f32_e32 v11, v11, v27
	v_add_f32_e32 v12, v12, v28
	v_add_f32_e32 v13, v13, v29
	v_add_f32_e32 v14, v14, v30
	v_add_f32_e32 v15, v15, v31
	s_barrier
	ds_write2st64_b32 v43, v0, v1 offset1:1
	ds_write2st64_b32 v43, v2, v3 offset0:2 offset1:3
	ds_write2st64_b32 v43, v4, v5 offset0:4 offset1:5
	ds_write2st64_b32 v43, v6, v7 offset0:6 offset1:7
	ds_write2st64_b32 v43, v8, v9 offset0:8 offset1:9
	ds_write2st64_b32 v43, v10, v11 offset0:10 offset1:11
	ds_write2st64_b32 v43, v12, v13 offset0:12 offset1:13
	ds_write2st64_b32 v43, v14, v15 offset0:14 offset1:15
	s_waitcnt lgkmcnt(0)
	s_barrier
	ds_read2st64_b32 v[0:1], v44 offset1:1
	ds_read2st64_b32 v[2:3], v44 offset0:16 offset1:17
	ds_read2st64_b32 v[4:5], v44 offset0:32 offset1:33
	ds_read2st64_b32 v[6:7], v44 offset0:48 offset1:49
	ds_read2st64_b32 v[8:9], v44 offset0:18 offset1:19
	ds_read2st64_b32 v[10:11], v44 offset0:2 offset1:3
	s_waitcnt lgkmcnt(4)
	v_add_f32_e32 v0, v0, v2
	ds_read2st64_b32 v[12:13], v44 offset0:50 offset1:51
	ds_read2st64_b32 v[14:15], v44 offset0:34 offset1:35
	s_waitcnt lgkmcnt(5)
	v_add_f32_e32 v0, v0, v4
	s_waitcnt lgkmcnt(4)
	v_add_f32_e32 v4, v0, v6
	v_add_f32_e32 v0, v1, v3
	v_add_f32_e32 v0, v0, v5
	v_add_f32_e32 v5, v0, v7
	s_waitcnt lgkmcnt(2)
	v_add_f32_e32 v0, v10, v8
	s_lshl_b32 s12, s10, 5
	s_waitcnt lgkmcnt(0)
	v_add_f32_e32 v0, v0, v14
	s_lshl_b32 s11, s10, 3
	s_and_b32 s12, s12, 0x60
	v_add_f32_e32 v6, v0, v12
	v_add_f32_e32 v0, v11, v9
	v_add_f32_e32 v0, v0, v15
	v_add_u32_e32 v8, s12, v45
	s_and_b32 s11, s11, 0xe0
	v_add_f32_e32 v7, v0, v13
	v_add_u32_e32 v0, 0x4000, v8
	v_or_b32_e32 v1, s11, v42
	s_ashr_i32 s14, s10, 5
	v_lshlrev_b32_e32 v36, 1, v1
	v_ashrrev_i32_e32 v1, 31, v0
	v_mad_i64_i32 v[0:1], s[12:13], s14, v47, v[0:1]
	v_lshl_add_u64 v[2:3], s[4:5], 0, v[36:37]
	v_lshlrev_b64 v[0:1], 9, v[0:1]
	v_cvt_pk_bf16_f32 v4, v4, s0
	v_lshl_add_u64 v[0:1], v[2:3], 0, v[0:1]
	global_store_short v[0:1], v4, off
	v_add_u32_e32 v0, 0x4001, v8
	v_ashrrev_i32_e32 v1, 31, v0
	v_mad_i64_i32 v[0:1], s[12:13], s14, v47, v[0:1]
	v_lshlrev_b64 v[0:1], 9, v[0:1]
	v_cvt_pk_bf16_f32 v4, v5, s0
	v_lshl_add_u64 v[0:1], v[2:3], 0, v[0:1]
	global_store_short v[0:1], v4, off
	v_add_u32_e32 v0, 0x4002, v8
	v_ashrrev_i32_e32 v1, 31, v0
	v_mad_i64_i32 v[0:1], s[12:13], s14, v47, v[0:1]
	v_lshlrev_b64 v[0:1], 9, v[0:1]
	v_cvt_pk_bf16_f32 v4, v6, s0
	v_lshl_add_u64 v[0:1], v[2:3], 0, v[0:1]
	global_store_short v[0:1], v4, off
	v_add_u32_e32 v0, 0x4003, v8
	v_ashrrev_i32_e32 v1, 31, v0
	v_mad_i64_i32 v[0:1], s[12:13], s14, v47, v[0:1]
	v_readlane_b32 s12, v254, 12
	v_lshlrev_b64 v[0:1], 9, v[0:1]
	s_add_i32 s10, s10, s12
	s_add_i32 s6, s6, s7
	s_add_i32 s8, s8, s9
	v_cvt_pk_bf16_f32 v4, v7, s0
	v_lshl_add_u64 v[0:1], v[2:3], 0, v[0:1]
	s_cmpk_lt_i32 s10, 0x80
	v_readlane_b32 s13, v254, 13
	global_store_short v[0:1], v4, off
	s_cbranch_scc1 .LBB0_2135
	s_branch .LBB0_2138
.Lp9_dummy:
	s_barrier
	s_barrier

.LBB0_2295:
	v_readlane_b32 s0, v254, 10
	v_mov_b32_e32 v33, 0
	v_mov_b32_e32 v0, 0
	s_cmpk_gt_i32 s0, 0xff
	s_waitcnt lgkmcnt(0)
	s_barrier
	v_readlane_b32 s1, v254, 11
	s_cbranch_scc1 .LBB0_2300
	s_bitcmp1_b32 s0, 0
	s_cbranch_scc1 .Lp11_dummy
	s_lshr_b32 s0, s0, 1
	v_writelane_b32 v254, s0, 10
	v_mbcnt_lo_u32_b32 v0, -1, v0
	v_mbcnt_hi_u32_b32 v6, -1, v0
	v_readlane_b32 s8, v254, 7
	v_and_b32_e32 v3, 63, v6
	v_lshlrev_b32_e32 v3, 2, v3
	v_add_u32_e32 v2, s8, v6
	v_ashrrev_i32_e32 v7, 6, v2
	v_lshlrev_b32_e32 v0, 8, v7
	v_lshlrev_b32_e32 v4, 12, v7
	v_ashrrev_i32_e32 v1, 31, v0
	v_add3_u32 v47, s91, v4, v3
	v_lshlrev_b32_e32 v4, 10, v7
	v_and_b32_e32 v2, 0xffffffc0, v2
	v_lshrrev_b32_e32 v8, 1, v6
	v_add3_u32 v48, s91, v4, v3
	v_ashrrev_i32_e32 v3, 31, v2
	v_and_b32_e32 v32, 16, v8
	v_lshlrev_b64 v[0:1], 1, v[0:1]
	v_lshlrev_b64 v[2:3], 1, v[2:3]
	v_or_b32_e32 v0, v0, v32
	s_add_u32 s0, s14, 0x4000000
	v_lshl_add_u64 v[4:5], s[12:13], 0, v[2:3]
	v_lshl_add_u64 v[2:3], s[2:3], 0, v[2:3]
	v_lshl_add_u64 v[0:1], s[4:5], 0, v[0:1]
	s_mov_b64 s[2:3], 0x2300080
	v_readlane_b32 s10, v254, 0
	v_readlane_b32 s12, v254, 14
	s_addc_u32 s1, s15, 0
	v_lshl_add_u64 v[38:39], v[0:1], 0, s[2:3]
	s_lshl_b32 s2, s10, 3
	s_lshl_b32 s3, s12, 3
	v_lshl_add_u64 v[36:37], v[2:3], 0, v[32:33]
	v_lshrrev_b32_e32 v2, 3, v6
	s_add_i32 s8, s2, s3
	s_mov_b64 s[2:3], 0x117e0080
	v_and_b32_e32 v46, 31, v6
	v_and_b32_e32 v2, 4, v2
	v_readlane_b32 s11, v254, 1
	v_lshl_add_u64 v[40:41], v[0:1], 0, s[2:3]
	s_lshl_b32 s2, s10, 5
	s_lshl_b32 s3, s12, 5
	v_lshl_add_u64 v[34:35], v[4:5], 0, v[32:33]
	v_lshl_or_b32 v49, v7, 3, v2
	v_or_b32_e32 v50, 0x4000, v46
	s_lshl_b32 s9, s11, 4
	s_add_i32 s10, s2, s3
	s_lshl_b32 s11, s11, 6
	s_mov_b64 s[2:3], 0x100
	s_brev_b32 s12, 64
	s_mov_b32 s13, 0x2001000

.LBB0_2298:
	global_load_dwordx4 v[52:55], v[44:45], off offset:-128
	global_load_dwordx4 v[56:59], v[42:43], off offset:-128
	global_load_dwordx4 v[60:63], v[44:45], off offset:-96
	global_load_dwordx4 v[64:67], v[42:43], off offset:-96
	global_load_dwordx4 v[68:71], v[44:45], off offset:-64
	s_addk_i32 s14, 0x80
	s_cmpk_lt_u32 s14, 0xe0
	s_waitcnt vmcnt(3)
	v_mfma_f32_32x32x16_bf16 v[0:15], v[52:55], v[56:59], v[0:15]
	global_load_dwordx4 v[52:55], v[42:43], off offset:-64
	global_load_dwordx4 v[56:59], v[44:45], off offset:-32
	s_waitcnt vmcnt(3)
	v_mfma_f32_32x32x16_bf16 v[16:31], v[60:63], v[64:67], v[16:31]
	global_load_dwordx4 v[60:63], v[42:43], off offset:-32
	global_load_dwordx4 v[64:67], v[44:45], off
	s_waitcnt vmcnt(3)
	v_mfma_f32_32x32x16_bf16 v[0:15], v[68:71], v[52:55], v[0:15]
	global_load_dwordx4 v[52:55], v[42:43], off
	global_load_dwordx4 v[68:71], v[44:45], off offset:32
	s_waitcnt vmcnt(3)
	v_mfma_f32_32x32x16_bf16 v[16:31], v[56:59], v[60:63], v[16:31]
	global_load_dwordx4 v[56:59], v[42:43], off offset:32
	global_load_dwordx4 v[60:63], v[44:45], off offset:64
	global_load_dwordx4 v[72:75], v[44:45], off offset:96
	v_lshl_add_u64 v[44:45], v[44:45], 0, s[2:3]
	s_waitcnt vmcnt(4)
	v_mfma_f32_32x32x16_bf16 v[0:15], v[64:67], v[52:55], v[0:15]
	global_load_dwordx4 v[52:55], v[42:43], off offset:64
	s_waitcnt vmcnt(3)
	v_mfma_f32_32x32x16_bf16 v[16:31], v[68:71], v[56:59], v[16:31]
	global_load_dwordx4 v[56:59], v[42:43], off offset:96
	v_lshl_add_u64 v[42:43], v[42:43], 0, s[2:3]
	s_waitcnt vmcnt(1)
	v_mfma_f32_32x32x16_bf16 v[0:15], v[60:63], v[52:55], v[0:15]
	s_waitcnt vmcnt(0)
	v_mfma_f32_32x32x16_bf16 v[16:31], v[72:75], v[56:59], v[16:31]
	s_cbranch_scc1 .LBB0_2298
	v_readlane_b32 s16, v254, 10
	s_lshl_b32 s15, s16, 5
	s_and_b32 s15, s15, 0x60
	v_or_b32_e32 v32, s15, v50
	s_nop 6
	v_add_f32_e32 v0, v0, v16
	v_add_f32_e32 v1, v1, v17
	v_add_f32_e32 v8, v8, v24
	v_add_f32_e32 v9, v9, v25
	v_lshlrev_b32_e32 v32, 9, v32
	v_add_f32_e32 v2, v2, v18
	v_add_f32_e32 v3, v3, v19
	v_add_f32_e32 v4, v4, v20
	v_add_f32_e32 v5, v5, v21
	v_add_f32_e32 v6, v6, v22
	v_add_f32_e32 v7, v7, v23
	v_add_f32_e32 v10, v10, v26
	v_add_f32_e32 v11, v11, v27
	v_add_f32_e32 v12, v12, v28
	v_add_f32_e32 v13, v13, v29
	v_add_f32_e32 v14, v14, v30
	v_add_f32_e32 v15, v15, v31
	s_barrier
	ds_write2st64_b32 v47, v0, v1 offset1:1
	ds_write2st64_b32 v47, v2, v3 offset0:2 offset1:3
	ds_write2st64_b32 v47, v4, v5 offset0:4 offset1:5
	ds_write2st64_b32 v47, v6, v7 offset0:6 offset1:7
	ds_write2st64_b32 v47, v8, v9 offset0:8 offset1:9
	ds_write2st64_b32 v47, v10, v11 offset0:10 offset1:11
	ds_write2st64_b32 v47, v12, v13 offset0:12 offset1:13
	ds_write2st64_b32 v47, v14, v15 offset0:14 offset1:15
	v_lshl_add_u64 v[8:9], v[34:35], 0, v[32:33]
	s_waitcnt lgkmcnt(0)
	s_barrier
	global_load_dwordx4 v[0:3], v[8:9], off
	s_lshl_b32 s14, s16, 3
	s_andn2_b32 s14, s14, 31
	v_or_b32_e32 v42, s14, v46
	v_ashrrev_i32_e32 v43, 31, v42
	v_lshlrev_b64 v[4:5], 9, v[42:43]
	v_lshl_add_u64 v[10:11], v[36:37], 0, v[4:5]
	global_load_dwordx4 v[4:7], v[10:11], off
	global_load_dwordx4 v[16:19], v[8:9], off offset:32
	global_load_dwordx4 v[20:23], v[10:11], off offset:32
	global_load_dwordx4 v[52:55], v[8:9], off offset:64
	global_load_dwordx4 v[56:59], v[10:11], off offset:64
	global_load_dwordx4 v[60:63], v[8:9], off offset:96
	global_load_dwordx4 v[64:67], v[10:11], off offset:96
	v_add_u32_e32 v82, s15, v49
	v_ashrrev_i32_e32 v83, 31, v82
	v_lshlrev_b64 v[84:85], 11, v[82:83]
	v_lshl_add_u64 v[84:85], s[6:7], 0, v[84:85]
	v_lshl_add_u64 v[84:85], v[42:43], 1, v[84:85]
	ds_read2st64_b32 v[44:45], v48 offset1:1
	ds_read2st64_b32 v[68:69], v48 offset0:16 offset1:17
	ds_read2st64_b32 v[70:71], v48 offset0:18 offset1:19
	ds_read2st64_b32 v[72:73], v48 offset0:2 offset1:3
	ds_read2st64_b32 v[74:75], v48 offset0:32 offset1:33
	ds_read2st64_b32 v[76:77], v48 offset0:48 offset1:49
	ds_read2st64_b32 v[78:79], v48 offset0:50 offset1:51
	ds_read2st64_b32 v[80:81], v48 offset0:34 offset1:35
	s_waitcnt lgkmcnt(0)
	s_barrier
	v_readlane_b32 s14, v254, 12
	s_add_i32 s16, s16, s14
	v_readlane_b32 s15, v254, 13
	s_mov_b32 s14, s16
	v_readlane_b32 s17, v254, 11
	s_add_i32 s8, s8, s9
	s_add_i32 s10, s10, s11
	v_writelane_b32 v254, s14, 10
	s_cmpk_lt_i32 s16, 0x80
	s_waitcnt vmcnt(4)
	v_mfma_f32_32x32x16_bf16 v[16:31], v[16:19], v[20:23], 0
	v_writelane_b32 v254, s15, 11
	v_mfma_f32_32x32x16_bf16 v[0:15], v[0:3], v[4:7], 0
	s_waitcnt vmcnt(2)
	v_mfma_f32_32x32x16_bf16 v[0:15], v[52:55], v[56:59], v[0:15]
	v_add_co_u32_e32 v52, vcc, s12, v84
	s_nop 1
	v_addc_co_u32_e32 v53, vcc, 0, v85, vcc
	v_add_co_u32_e32 v54, vcc, s13, v84
	s_waitcnt vmcnt(0)
	v_mfma_f32_32x32x16_bf16 v[16:31], v[60:63], v[64:67], v[16:31]
	v_addc_co_u32_e32 v55, vcc, 0, v85, vcc
	s_nop 10
	v_add_f32_e32 v0, v0, v16
	v_add_f32_e32 v1, v1, v17
	v_add_f32_e32 v2, v2, v18
	v_add_f32_e32 v3, v3, v19
	v_add_f32_e32 v4, v4, v20
	v_add_f32_e32 v5, v5, v21
	v_add_f32_e32 v6, v6, v22
	v_add_f32_e32 v7, v7, v23
	v_add_f32_e32 v8, v8, v24
	v_add_f32_e32 v9, v9, v25
	v_add_f32_e32 v10, v10, v26
	v_add_f32_e32 v11, v11, v27
	v_add_f32_e32 v12, v12, v28
	v_add_f32_e32 v13, v13, v29
	v_add_f32_e32 v14, v14, v30
	v_add_f32_e32 v15, v15, v31
	ds_write2st64_b32 v47, v0, v1 offset1:1
	ds_write2st64_b32 v47, v2, v3 offset0:2 offset1:3
	ds_write2st64_b32 v47, v4, v5 offset0:4 offset1:5
	ds_write2st64_b32 v47, v6, v7 offset0:6 offset1:7
	ds_write2st64_b32 v47, v8, v9 offset0:8 offset1:9
	ds_write2st64_b32 v47, v10, v11 offset0:10 offset1:11
	ds_write2st64_b32 v47, v12, v13 offset0:12 offset1:13
	ds_write2st64_b32 v47, v14, v15 offset0:14 offset1:15
	s_waitcnt lgkmcnt(0)
	s_barrier
	global_load_ushort v24, v[54:55], off offset:-4096
	global_load_ushort v25, v[54:55], off
	global_load_ushort v26, v[54:55], off offset:2048
	global_load_ushort v27, v[52:53], off offset:2048
	v_or_b32_e32 v0, 1, v82
	v_or_b32_e32 v2, 2, v82
	v_or_b32_e32 v4, 3, v82
	v_ashrrev_i32_e32 v1, 31, v0
	v_ashrrev_i32_e32 v3, 31, v2
	v_ashrrev_i32_e32 v5, 31, v4
	v_lshl_add_u64 v[6:7], v[42:43], 2, s[0:1]
	v_lshlrev_b64 v[8:9], 12, v[82:83]
	v_lshlrev_b64 v[0:1], 12, v[0:1]
	v_lshlrev_b64 v[2:3], 12, v[2:3]
	v_lshlrev_b64 v[4:5], 12, v[4:5]
	v_add_f32_e32 v10, v44, v68
	v_add_f32_e32 v11, v45, v69
	v_add_f32_e32 v12, v72, v70
	v_add_f32_e32 v13, v73, v71
	v_lshl_add_u64 v[8:9], v[6:7], 0, v[8:9]
	v_lshl_add_u64 v[0:1], v[6:7], 0, v[0:1]
	v_lshl_add_u64 v[2:3], v[6:7], 0, v[2:3]
	v_lshl_add_u64 v[4:5], v[6:7], 0, v[4:5]
	v_add_f32_e32 v6, v10, v74
	v_add_f32_e32 v7, v11, v75
	v_add_f32_e32 v10, v12, v80
	v_add_f32_e32 v11, v13, v81
	v_add_f32_e32 v6, v6, v76
	v_add_f32_e32 v7, v7, v77
	v_add_f32_e32 v10, v10, v78
	v_add_f32_e32 v11, v11, v79
	v_mul_f32_e32 v6, 0xbfb8aa3b, v6
	v_mul_f32_e32 v7, 0xbfb8aa3b, v7
	v_mul_f32_e32 v10, 0xbfb8aa3b, v10
	v_mul_f32_e32 v11, 0xbfb8aa3b, v11
	v_exp_f32_e32 v6, v6
	v_exp_f32_e32 v7, v7
	v_exp_f32_e32 v10, v10
	v_exp_f32_e32 v11, v11
	v_add_f32_e32 v6, 1.0, v6
	v_add_f32_e32 v7, 1.0, v7
	v_add_f32_e32 v10, 1.0, v10
	v_add_f32_e32 v11, 1.0, v11
	v_rcp_f32_e32 v28, v6
	v_rcp_f32_e32 v29, v7
	v_rcp_f32_e32 v30, v10
	v_rcp_f32_e32 v31, v11
	ds_read2st64_b32 v[6:7], v48 offset1:1
	ds_read2st64_b32 v[10:11], v48 offset0:16 offset1:17
	ds_read2st64_b32 v[12:13], v48 offset0:18 offset1:19
	ds_read2st64_b32 v[14:15], v48 offset0:2 offset1:3
	ds_read2st64_b32 v[16:17], v48 offset0:32 offset1:33
	ds_read2st64_b32 v[18:19], v48 offset0:48 offset1:49
	ds_read2st64_b32 v[20:21], v48 offset0:50 offset1:51
	ds_read2st64_b32 v[22:23], v48 offset0:34 offset1:35
	s_waitcnt lgkmcnt(6)
	v_add_f32_e32 v6, v6, v10
	v_add_f32_e32 v7, v7, v11
	s_waitcnt lgkmcnt(4)
	v_add_f32_e32 v10, v14, v12
	v_add_f32_e32 v11, v15, v13
	s_waitcnt lgkmcnt(3)
	v_add_f32_e32 v6, v6, v16
	v_add_f32_e32 v7, v7, v17
	s_waitcnt lgkmcnt(0)
	v_add_f32_e32 v10, v10, v22
	v_add_f32_e32 v11, v11, v23
	v_add_f32_e32 v6, v6, v18
	v_add_f32_e32 v7, v7, v19
	v_add_f32_e32 v10, v10, v20
	v_add_f32_e32 v11, v11, v21
	s_waitcnt vmcnt(3)
	v_lshlrev_b32_e32 v12, 16, v24
	s_waitcnt vmcnt(2)
	v_lshlrev_b32_e32 v14, 16, v25
	s_waitcnt vmcnt(1)
	v_lshlrev_b32_e32 v15, 16, v26
	s_waitcnt vmcnt(0)
	v_lshlrev_b32_e32 v13, 16, v27
	v_fmac_f32_e32 v12, v28, v6
	v_fmac_f32_e32 v13, v29, v7
	v_fmac_f32_e32 v14, v30, v10
	v_fmac_f32_e32 v15, v31, v11
	global_store_dword v[8:9], v12, off
	global_store_dword v[0:1], v13, off
	global_store_dword v[2:3], v14, off
	global_store_dword v[4:5], v15, off
	s_cbranch_scc1 .LBB0_2297
	s_branch .LBB0_2300
